# K-loop heads aligned to 64 bytes (on saddr + equal priority + peeled iteration)
# speedup vs baseline: 1.0021x; 1.0021x over previous
; #define PG8_STAGE(bufoff, gbase, voff) do { _Pragma("unroll") for (int _i = 0; _i < 2; ++_i) \
;         __builtin_amdgcn_global_load_lds((const unsigned*)((const char*)(gbase) + (voff)[_i]), (LAS unsigned*)(lds + (bufoff) + ldsw + _i * 8192), 16, 0, 0); } while (0)
; #define PG8_LDA(dst, b, h) do { _Pragma("unroll") for (int m = 0; m < 4; ++m) _Pragma("unroll") for (int k = 0; k < 2; ++k) dst[m][k] = *(const LAS bf16x8*)(lds + PG8_SA(b, h) + aoff + m * 2048 + k * 1024); } while (0)
; #define PG8_LDB(dst, b, h) do { _Pragma("unroll") for (int n = 0; n < 2; ++n) _Pragma("unroll") for (int k = 0; k < 2; ++k) dst[n][k] = *(const LAS bf16x8*)(lds + PG8_SB(b, h) + boff + n * 2048 + k * 1024); } while (0)
; #define PG8_WAIT_V(n) asm volatile("s_waitcnt vmcnt(" #n ")" ::: "memory")
; #define PG8_WAIT_L(n) asm volatile("s_waitcnt lgkmcnt(" #n ")" ::: "memory")
; #define PG8_BAR __builtin_amdgcn_s_barrier()
; #define PG8_SCHED __builtin_amdgcn_sched_barrier(0)
; template <class Epi, class Sched, int KC, bool ALIGN_EPI = false, bool SP2 = false, bool ATILED = false>
; __device__ __forceinline__ void gemm_phase(LAS unsigned char* lds, const Gemm g, const Sched& S, const Epi& E, int wave_s) {
;     ...
;         const bool has_next = S.next(ui + 1, nxt);
;         const char* nA = has_next ? (const char*)g.A + (size_t)nxt.pm * tstepA : cA; const char* nB = has_next ? (const char*)g.Bt + (size_t)nxt.pn * tstep : cB;
;         for (int t = 0; t < nt; t += 2) {
;             const bool last = (t == nt - 2);
;             const char* a1 = cA + PG8_AOFF(t + 1);
;             const char* a2 = last ? nA : cA + PG8_AOFF(t + 2); const char* b2 = last ? nB : cB + (size_t)(t + 2) * kstep;
;             const char* a3 = a2 + kstep; const char* b3 = b2 + kstep;
;             if (last && has_next) S.a_ready(nxt);
;             if constexpr (SP2) {
;             PG8_LDB(B0, 0, 0); PG8_LDB(B1, 0, 1); PG8_SCHED; PG8_LDA(At, 0, 0); PG8_STAGE(PG8_SA(1, 1), a1 + hstepA, voffA);
;             PG8_WAIT_V(8); PG8_WAIT_L(0); PG8_BAR; PG8_MMA(0, 0, At, B0); PG8_MMA(0, 1, At, B1); PG8_BAR; PG8_SCHED;
;     ...
; #pragma unroll
;         for (int a = 0; a < 2; ++a)
; #pragma unroll
;             for (int b = 0; b < 2; ++b)
; #pragma unroll
;                 for (int m = 0; m < 4; ++m)
; #pragma unroll
;                     for (int n = 0; n < 2; ++n) acc[a][b][m][n] = (f32x4){0.f, 0.f, 0.f, 0.f};
.LBB0_232:
	s_ashr_i32 s19, s18, 31
	s_lshl_b64 s[20:21], s[18:19], 17
	s_add_u32 s20, s39, s20
	s_addc_u32 s21, s40, s21
	s_and_b64 s[22:23], s[6:7], exec
	s_cselect_b32 s19, s21, s27
	s_cselect_b32 s53, s20, s26
	s_ashr_i32 s17, s16, 31
	s_lshl_b64 s[22:23], s[16:17], 20
	s_add_u32 s22, s41, s22
	s_addc_u32 s23, s42, s23
	s_and_b64 s[30:31], s[6:7], exec
	s_cselect_b32 s17, s23, s29
	s_cselect_b32 s54, s22, s28
	s_add_u32 s55, s28, 0x100
	v_mov_b32_e32 v2, 0
	s_addc_u32 s56, s29, 0
	s_mov_b32 s57, -2
	s_mov_b64 s[28:29], 0
	s_mov_b32 s58, 0x400000
	v_mov_b32_e32 v3, v2
	v_mov_b32_e32 v4, v2
	v_mov_b32_e32 v5, v2
	v_mov_b32_e32 v14, v2
	v_mov_b32_e32 v15, v2
	v_mov_b32_e32 v16, v2
	v_mov_b32_e32 v17, v2
	v_mov_b32_e32 v22, v2
	v_mov_b32_e32 v23, v2
	v_mov_b32_e32 v24, v2
	v_mov_b32_e32 v25, v2
	v_mov_b32_e32 v30, v2
	v_mov_b32_e32 v31, v2
	v_mov_b32_e32 v32, v2
	v_mov_b32_e32 v33, v2
	v_mov_b32_e32 v38, v2
	v_mov_b32_e32 v39, v2
	v_mov_b32_e32 v40, v2
	v_mov_b32_e32 v41, v2
	v_mov_b32_e32 v46, v2
	v_mov_b32_e32 v47, v2
	v_mov_b32_e32 v48, v2
	v_mov_b32_e32 v49, v2
	v_mov_b32_e32 v54, v2
	v_mov_b32_e32 v55, v2
	v_mov_b32_e32 v56, v2
	v_mov_b32_e32 v57, v2
	v_mov_b32_e32 v62, v2
	v_mov_b32_e32 v63, v2
	v_mov_b32_e32 v64, v2
	v_mov_b32_e32 v65, v2
	v_mov_b32_e32 v6, v2
	v_mov_b32_e32 v7, v2
	v_mov_b32_e32 v8, v2
	v_mov_b32_e32 v9, v2
	v_mov_b32_e32 v10, v2
	v_mov_b32_e32 v11, v2
	v_mov_b32_e32 v12, v2
	v_mov_b32_e32 v13, v2
	v_mov_b32_e32 v18, v2
	v_mov_b32_e32 v19, v2
	v_mov_b32_e32 v20, v2
	v_mov_b32_e32 v21, v2
	v_mov_b32_e32 v26, v2
	v_mov_b32_e32 v27, v2
	v_mov_b32_e32 v28, v2
	v_mov_b32_e32 v29, v2
	v_mov_b32_e32 v34, v2
	v_mov_b32_e32 v35, v2
	v_mov_b32_e32 v36, v2
	v_mov_b32_e32 v37, v2
	v_mov_b32_e32 v42, v2
	v_mov_b32_e32 v43, v2
	v_mov_b32_e32 v44, v2
	v_mov_b32_e32 v45, v2
	v_mov_b32_e32 v50, v2
	v_mov_b32_e32 v51, v2
	v_mov_b32_e32 v52, v2
	v_mov_b32_e32 v53, v2
	v_mov_b32_e32 v58, v2
	v_mov_b32_e32 v59, v2
	v_mov_b32_e32 v60, v2
	v_mov_b32_e32 v61, v2
	v_mov_b32_e32 v70, v2
	v_mov_b32_e32 v71, v2
	v_mov_b32_e32 v72, v2
	v_mov_b32_e32 v73, v2
	v_mov_b32_e32 v78, v2
	v_mov_b32_e32 v79, v2
	v_mov_b32_e32 v80, v2
	v_mov_b32_e32 v81, v2
	v_mov_b32_e32 v86, v2
	v_mov_b32_e32 v87, v2
	v_mov_b32_e32 v88, v2
	v_mov_b32_e32 v89, v2
	v_mov_b32_e32 v94, v2
	v_mov_b32_e32 v95, v2
	v_mov_b32_e32 v96, v2
	v_mov_b32_e32 v97, v2
	v_mov_b32_e32 v102, v2
	v_mov_b32_e32 v103, v2
	v_mov_b32_e32 v104, v2
	v_mov_b32_e32 v105, v2
	v_mov_b32_e32 v110, v2
	v_mov_b32_e32 v111, v2
	v_mov_b32_e32 v112, v2
	v_mov_b32_e32 v113, v2
	v_mov_b32_e32 v118, v2
	v_mov_b32_e32 v119, v2
	v_mov_b32_e32 v120, v2
	v_mov_b32_e32 v121, v2
	v_mov_b32_e32 v126, v2
	v_mov_b32_e32 v127, v2
	v_mov_b32_e32 v128, v2
	v_mov_b32_e32 v129, v2
	v_mov_b32_e32 v66, v2
	v_mov_b32_e32 v67, v2
	v_mov_b32_e32 v68, v2
	v_mov_b32_e32 v69, v2
	v_mov_b32_e32 v74, v2
	v_mov_b32_e32 v75, v2
	v_mov_b32_e32 v76, v2
	v_mov_b32_e32 v77, v2
	v_mov_b32_e32 v82, v2
	v_mov_b32_e32 v83, v2
	v_mov_b32_e32 v84, v2
	v_mov_b32_e32 v85, v2
	v_mov_b32_e32 v90, v2
	v_mov_b32_e32 v91, v2
	v_mov_b32_e32 v92, v2
	v_mov_b32_e32 v93, v2
	v_mov_b32_e32 v98, v2
	v_mov_b32_e32 v99, v2
	v_mov_b32_e32 v100, v2
	v_mov_b32_e32 v101, v2
	v_mov_b32_e32 v106, v2
	v_mov_b32_e32 v107, v2
	v_mov_b32_e32 v108, v2
	v_mov_b32_e32 v109, v2
	v_mov_b32_e32 v114, v2
	v_mov_b32_e32 v115, v2
	v_mov_b32_e32 v116, v2
	v_mov_b32_e32 v117, v2
	v_mov_b32_e32 v122, v2
	v_mov_b32_e32 v123, v2
	v_mov_b32_e32 v124, v2
	v_mov_b32_e32 v125, v2
	s_add_i32 s30, s58, 0xffc00000
	s_and_b32 s30, s30, 0x3800000
	s_and_b32 s31, s28, 0x100
	s_or_b32 s59, s31, s30
	s_and_b32 s34, s58, 0x7800000
	s_add_u32 s30, s28, 0x100
	s_addc_u32 s31, s29, 0
	s_and_b32 s35, s30, 0x100
	s_or_b32 s34, s34, s35
	s_add_u32 s34, s26, s34
	s_addc_u32 s35, s27, 0
	s_add_u32 s28, s55, s28
	s_addc_u32 s29, s56, s29
	s_add_i32 s62, 0, 0x10000
	s_cmp_eq_u32 s57, 28
	s_cselect_b32 s35, s19, s35
	s_cselect_b32 s34, s53, s34
	v_add_u32_e32 v139, s62, v163
	s_cselect_b32 s29, s17, s29
	s_cselect_b32 s28, s54, s28
	s_add_i32 s63, 0, 0x14000
	ds_read_b128 v[152:155], v139
	ds_read_b128 v[156:159], v139 offset:1024
	ds_read_b128 v[168:171], v139 offset:2048
	ds_read_b128 v[172:175], v139 offset:3072
	v_add_u32_e32 v139, s63, v163
	ds_read_b128 v[176:179], v139
	ds_read_b128 v[180:183], v139 offset:1024
	ds_read_b128 v[184:187], v139 offset:2048
	ds_read_b128 v[188:191], v139 offset:3072
	s_add_u32 s59, s26, s59
	s_addc_u32 s61, s27, 0
	s_add_u32 s60, s59, 0x10080
	s_addc_u32 s61, s61, 0
	s_add_i32 m0, s44, 0xc000
	ds_read_b128 v[198:201], v166
	ds_read_b128 v[202:205], v166 offset:1024
	ds_read_b128 v[206:209], v166 offset:2048
	ds_read_b128 v[210:213], v166 offset:3072
	ds_read_b128 v[214:217], v166 offset:4096
	ds_read_b128 v[218:221], v166 offset:5120
	ds_read_b128 v[222:225], v166 offset:6144
	ds_read_b128 v[226:229], v166 offset:7168
	global_load_lds_dwordx4 v136, s[60:61]
	s_add_i32 m0, s44, 0xe000
	s_nop 0
	global_load_lds_dwordx4 v132, s[60:61]
	s_waitcnt vmcnt(16)
	s_waitcnt lgkmcnt(0)
	s_barrier
; #define PG8_STAGE(bufoff, gbase, voff) do { _Pragma("unroll") for (int _i = 0; _i < 2; ++_i) \
;         __builtin_amdgcn_global_load_lds((const unsigned*)((const char*)(gbase) + (voff)[_i]), (LAS unsigned*)(lds + (bufoff) + ldsw + _i * 8192), 16, 0, 0); } while (0)
; #define PG8_LDA(dst, b, h) do { _Pragma("unroll") for (int m = 0; m < 4; ++m) _Pragma("unroll") for (int k = 0; k < 2; ++k) dst[m][k] = *(const LAS bf16x8*)(lds + PG8_SA(b, h) + aoff + m * 2048 + k * 1024); } while (0)
; #define PG8_LDB(dst, b, h) do { _Pragma("unroll") for (int n = 0; n < 2; ++n) _Pragma("unroll") for (int k = 0; k < 2; ++k) dst[n][k] = *(const LAS bf16x8*)(lds + PG8_SB(b, h) + boff + n * 2048 + k * 1024); } while (0)
; #define PG8_MMA(ai, bj, At, Bt) do { __builtin_amdgcn_s_setprio(1); _Pragma("unroll") for (int m = 0; m < 4; ++m) _Pragma("unroll") for (int n = 0; n < 2; ++n) _Pragma("unroll") for (int k = 0; k < 2; ++k) \
;         acc[ai][bj][m][n] = __builtin_amdgcn_mfma_f32_16x16x32_bf16(Bt[n][k], At[m][k], acc[ai][bj][m][n], 0, 0, 0); __builtin_amdgcn_s_setprio(0); } while (0)
; #define PG8_WAIT_V(n) asm volatile("s_waitcnt vmcnt(" #n ")" ::: "memory")
; #define PG8_WAIT_L(n) asm volatile("s_waitcnt lgkmcnt(" #n ")" ::: "memory")
; #define PG8_BAR __builtin_amdgcn_s_barrier()
; #define PG8_SCHED __builtin_amdgcn_sched_barrier(0)
; template <class Epi, class Sched, int KC, bool ALIGN_EPI = false, bool SP2 = false, bool ATILED = false>
; __device__ __forceinline__ void gemm_phase(LAS unsigned char* lds, const Gemm g, const Sched& S, const Epi& E, int wave_s) {
;     ...
;             PG8_WAIT_V(8); PG8_WAIT_L(0); PG8_BAR; PG8_MMA(0, 0, At, B0); PG8_MMA(0, 1, At, B1); PG8_BAR; PG8_SCHED;
;             PG8_LDA(At, 0, 1); PG8_STAGE(PG8_SB(0, 0), b2, voffB); PG8_STAGE(PG8_SB(0, 1), b2 + hstepB, voffB); PG8_STAGE(PG8_SA(0, 0), a2, voffA);
;             PG8_WAIT_V(8); PG8_WAIT_L(0); PG8_BAR; PG8_MMA(1, 0, At, B0); PG8_MMA(1, 1, At, B1); PG8_BAR; PG8_SCHED;
;             PG8_LDB(B0, 1, 0); PG8_LDB(B1, 1, 1); PG8_SCHED; PG8_LDA(At, 1, 0); PG8_STAGE(PG8_SA(0, 1), a2 + hstepA, voffA);
	s_waitcnt lgkmcnt(0)
	v_mfma_f32_16x16x32_bf16 v[122:125], v[152:155], v[198:201], v[122:125]
	v_mfma_f32_16x16x32_bf16 v[114:117], v[168:171], v[198:201], v[114:117]
	v_mfma_f32_16x16x32_bf16 v[106:109], v[152:155], v[206:209], v[106:109]
	v_mfma_f32_16x16x32_bf16 v[98:101], v[168:171], v[206:209], v[98:101]
	v_mfma_f32_16x16x32_bf16 v[90:93], v[152:155], v[214:217], v[90:93]
	v_mfma_f32_16x16x32_bf16 v[82:85], v[168:171], v[214:217], v[82:85]
	v_mfma_f32_16x16x32_bf16 v[74:77], v[152:155], v[222:225], v[74:77]
	v_mfma_f32_16x16x32_bf16 v[66:69], v[168:171], v[222:225], v[66:69]
	v_mfma_f32_16x16x32_bf16 v[122:125], v[156:159], v[202:205], v[122:125]
	v_mfma_f32_16x16x32_bf16 v[114:117], v[172:175], v[202:205], v[114:117]
	v_mfma_f32_16x16x32_bf16 v[106:109], v[156:159], v[210:213], v[106:109]
	v_mfma_f32_16x16x32_bf16 v[98:101], v[172:175], v[210:213], v[98:101]
	v_mfma_f32_16x16x32_bf16 v[90:93], v[156:159], v[218:221], v[90:93]
	v_mfma_f32_16x16x32_bf16 v[82:85], v[172:175], v[218:221], v[82:85]
	v_mfma_f32_16x16x32_bf16 v[74:77], v[156:159], v[226:229], v[74:77]
	v_mfma_f32_16x16x32_bf16 v[66:69], v[172:175], v[226:229], v[66:69]
	v_mfma_f32_16x16x32_bf16 v[126:129], v[176:179], v[198:201], v[126:129]
	v_mfma_f32_16x16x32_bf16 v[118:121], v[184:187], v[198:201], v[118:121]
	v_mfma_f32_16x16x32_bf16 v[110:113], v[176:179], v[206:209], v[110:113]
	v_mfma_f32_16x16x32_bf16 v[102:105], v[184:187], v[206:209], v[102:105]
	v_mfma_f32_16x16x32_bf16 v[94:97], v[176:179], v[214:217], v[94:97]
	v_mfma_f32_16x16x32_bf16 v[86:89], v[184:187], v[214:217], v[86:89]
	v_mfma_f32_16x16x32_bf16 v[78:81], v[176:179], v[222:225], v[78:81]
	v_mfma_f32_16x16x32_bf16 v[70:73], v[184:187], v[222:225], v[70:73]
	v_mfma_f32_16x16x32_bf16 v[126:129], v[180:183], v[202:205], v[126:129]
	v_mfma_f32_16x16x32_bf16 v[118:121], v[188:191], v[202:205], v[118:121]
	v_mfma_f32_16x16x32_bf16 v[110:113], v[180:183], v[210:213], v[110:113]
	v_mfma_f32_16x16x32_bf16 v[102:105], v[188:191], v[210:213], v[102:105]
	v_mfma_f32_16x16x32_bf16 v[94:97], v[180:183], v[218:221], v[94:97]
	v_mfma_f32_16x16x32_bf16 v[86:89], v[188:191], v[218:221], v[86:89]
	v_mfma_f32_16x16x32_bf16 v[78:81], v[180:183], v[226:229], v[78:81]
	v_mfma_f32_16x16x32_bf16 v[70:73], v[188:191], v[226:229], v[70:73]
	s_barrier
	s_add_u32 s100, s34, 0x80
	s_addc_u32 s101, s35, 0
	s_add_i32 s59, s62, s38
	s_mov_b32 m0, s59
	ds_read_b128 v[198:201], v166 offset:16384
	ds_read_b128 v[202:205], v166 offset:17408
	ds_read_b128 v[206:209], v166 offset:18432
	ds_read_b128 v[210:213], v166 offset:19456
	ds_read_b128 v[214:217], v166 offset:20480
	ds_read_b128 v[218:221], v166 offset:21504
	ds_read_b128 v[222:225], v166 offset:22528
	ds_read_b128 v[226:229], v166 offset:23552
	global_load_lds_dwordx4 v134, s[28:29]
	s_add_i32 m0, s59, 0x2000
	s_add_u32 s60, s28, 0x80000
	s_addc_u32 s61, s29, 0
	s_add_i32 s59, s63, s38
	global_load_lds_dwordx4 v130, s[28:29]
	s_mov_b32 m0, s59
	s_nop 0
	global_load_lds_dwordx4 v134, s[60:61]
	s_add_i32 m0, s59, 0x2000
	s_nop 0
	global_load_lds_dwordx4 v130, s[60:61]
	s_mov_b32 m0, s44
	s_nop 0
	global_load_lds_dwordx4 v136, s[34:35]
	s_mov_b32 m0, s45
	s_nop 0
	global_load_lds_dwordx4 v132, s[34:35]
	s_waitcnt vmcnt(16)
	s_waitcnt lgkmcnt(0)
	s_barrier
	s_waitcnt lgkmcnt(0)
	v_mfma_f32_16x16x32_bf16 v[58:61], v[152:155], v[198:201], v[58:61]
	v_mfma_f32_16x16x32_bf16 v[50:53], v[168:171], v[198:201], v[50:53]
	v_mfma_f32_16x16x32_bf16 v[42:45], v[152:155], v[206:209], v[42:45]
	v_mfma_f32_16x16x32_bf16 v[34:37], v[168:171], v[206:209], v[34:37]
	v_mfma_f32_16x16x32_bf16 v[26:29], v[152:155], v[214:217], v[26:29]
	v_mfma_f32_16x16x32_bf16 v[18:21], v[168:171], v[214:217], v[18:21]
	v_mfma_f32_16x16x32_bf16 v[10:13], v[152:155], v[222:225], v[10:13]
	v_mfma_f32_16x16x32_bf16 v[6:9], v[168:171], v[222:225], v[6:9]
	v_mfma_f32_16x16x32_bf16 v[58:61], v[156:159], v[202:205], v[58:61]
	v_mfma_f32_16x16x32_bf16 v[50:53], v[172:175], v[202:205], v[50:53]
	v_mfma_f32_16x16x32_bf16 v[42:45], v[156:159], v[210:213], v[42:45]
	v_mfma_f32_16x16x32_bf16 v[34:37], v[172:175], v[210:213], v[34:37]
	v_mfma_f32_16x16x32_bf16 v[26:29], v[156:159], v[218:221], v[26:29]
	v_mfma_f32_16x16x32_bf16 v[18:21], v[172:175], v[218:221], v[18:21]
	v_mfma_f32_16x16x32_bf16 v[10:13], v[156:159], v[226:229], v[10:13]
	v_mfma_f32_16x16x32_bf16 v[6:9], v[172:175], v[226:229], v[6:9]
	v_mfma_f32_16x16x32_bf16 v[62:65], v[176:179], v[198:201], v[62:65]
	v_mfma_f32_16x16x32_bf16 v[54:57], v[184:187], v[198:201], v[54:57]
	v_mfma_f32_16x16x32_bf16 v[46:49], v[176:179], v[206:209], v[46:49]
	v_mfma_f32_16x16x32_bf16 v[38:41], v[184:187], v[206:209], v[38:41]
	v_mfma_f32_16x16x32_bf16 v[30:33], v[176:179], v[214:217], v[30:33]
	v_mfma_f32_16x16x32_bf16 v[22:25], v[184:187], v[214:217], v[22:25]
	v_mfma_f32_16x16x32_bf16 v[14:17], v[176:179], v[222:225], v[14:17]
	v_mfma_f32_16x16x32_bf16 v[2:5], v[184:187], v[222:225], v[2:5]
	v_mfma_f32_16x16x32_bf16 v[62:65], v[180:183], v[202:205], v[62:65]
	v_mfma_f32_16x16x32_bf16 v[54:57], v[188:191], v[202:205], v[54:57]
	v_mfma_f32_16x16x32_bf16 v[46:49], v[180:183], v[210:213], v[46:49]
	v_mfma_f32_16x16x32_bf16 v[38:41], v[188:191], v[210:213], v[38:41]
	v_mfma_f32_16x16x32_bf16 v[30:33], v[180:183], v[218:221], v[30:33]
	v_mfma_f32_16x16x32_bf16 v[22:25], v[188:191], v[218:221], v[22:25]
	v_mfma_f32_16x16x32_bf16 v[14:17], v[180:183], v[226:229], v[14:17]
	v_mfma_f32_16x16x32_bf16 v[2:5], v[188:191], v[226:229], v[2:5]
	s_barrier
; #define PG8_STAGE(bufoff, gbase, voff) do { _Pragma("unroll") for (int _i = 0; _i < 2; ++_i) \
;         __builtin_amdgcn_global_load_lds((const unsigned*)((const char*)(gbase) + (voff)[_i]), (LAS unsigned*)(lds + (bufoff) + ldsw + _i * 8192), 16, 0, 0); } while (0)
; #define PG8_LDA(dst, b, h) do { _Pragma("unroll") for (int m = 0; m < 4; ++m) _Pragma("unroll") for (int k = 0; k < 2; ++k) dst[m][k] = *(const LAS bf16x8*)(lds + PG8_SA(b, h) + aoff + m * 2048 + k * 1024); } while (0)
; #define PG8_LDB(dst, b, h) do { _Pragma("unroll") for (int n = 0; n < 2; ++n) _Pragma("unroll") for (int k = 0; k < 2; ++k) dst[n][k] = *(const LAS bf16x8*)(lds + PG8_SB(b, h) + boff + n * 2048 + k * 1024); } while (0)
; #define PG8_MMA(ai, bj, At, Bt) do { __builtin_amdgcn_s_setprio(1); _Pragma("unroll") for (int m = 0; m < 4; ++m) _Pragma("unroll") for (int n = 0; n < 2; ++n) _Pragma("unroll") for (int k = 0; k < 2; ++k) \
;         acc[ai][bj][m][n] = __builtin_amdgcn_mfma_f32_16x16x32_bf16(Bt[n][k], At[m][k], acc[ai][bj][m][n], 0, 0, 0); __builtin_amdgcn_s_setprio(0); } while (0)
; #define PG8_WAIT_V(n) asm volatile("s_waitcnt vmcnt(" #n ")" ::: "memory")
; #define PG8_WAIT_L(n) asm volatile("s_waitcnt lgkmcnt(" #n ")" ::: "memory")
; #define PG8_BAR __builtin_amdgcn_s_barrier()
; #define PG8_SCHED __builtin_amdgcn_sched_barrier(0)
; template <class Epi, class Sched, int KC, bool ALIGN_EPI = false, bool SP2 = false, bool ATILED = false>
; __device__ __forceinline__ void gemm_phase(LAS unsigned char* lds, const Gemm g, const Sched& S, const Epi& E, int wave_s) {
;     ...
;             PG8_LDB(B0, 1, 0); PG8_LDB(B1, 1, 1); PG8_SCHED; PG8_LDA(At, 1, 0); PG8_STAGE(PG8_SA(0, 1), a2 + hstepA, voffA);
;             PG8_WAIT_V(8); PG8_WAIT_L(0); PG8_BAR; PG8_MMA(0, 0, At, B0); PG8_MMA(0, 1, At, B1); PG8_BAR; PG8_SCHED;
;             PG8_LDA(At, 1, 1); PG8_STAGE(PG8_SB(1, 0), b3, voffB); PG8_STAGE(PG8_SB(1, 1), b3 + hstepB, voffB); PG8_STAGE(PG8_SA(1, 0), a3, voffA);
;             PG8_WAIT_V(8); PG8_WAIT_L(0); PG8_BAR; PG8_MMA(1, 0, At, B0); PG8_MMA(1, 1, At, B1); PG8_BAR; PG8_SCHED;
	s_add_i32 s59, 0, 0x18000
	v_add_u32_e32 v139, s59, v163
	s_add_i32 s60, 0, 0x1c000
	ds_read_b128 v[152:155], v139
	ds_read_b128 v[156:159], v139 offset:1024
	ds_read_b128 v[168:171], v139 offset:2048
	ds_read_b128 v[172:175], v139 offset:3072
	v_add_u32_e32 v139, s60, v163
	ds_read_b128 v[176:179], v139
	ds_read_b128 v[180:183], v139 offset:1024
	ds_read_b128 v[184:187], v139 offset:2048
	ds_read_b128 v[188:191], v139 offset:3072
	s_add_u32 s34, s34, 0x10000
	s_addc_u32 s35, s35, 0
	s_mov_b32 m0, s46
	ds_read_b128 v[198:201], v166 offset:32768
	ds_read_b128 v[202:205], v166 offset:33792
	ds_read_b128 v[206:209], v166 offset:34816
	ds_read_b128 v[210:213], v166 offset:35840
	ds_read_b128 v[214:217], v166 offset:36864
	ds_read_b128 v[218:221], v166 offset:37888
	ds_read_b128 v[222:225], v166 offset:38912
	ds_read_b128 v[226:229], v166 offset:39936
	global_load_lds_dwordx4 v136, s[34:35]
	s_mov_b32 m0, s47
	s_nop 0
	global_load_lds_dwordx4 v132, s[34:35]
	s_waitcnt vmcnt(8)
	s_waitcnt lgkmcnt(0)
	s_barrier
	s_waitcnt lgkmcnt(0)
	v_mfma_f32_16x16x32_bf16 v[122:125], v[152:155], v[198:201], v[122:125]
	v_mfma_f32_16x16x32_bf16 v[114:117], v[168:171], v[198:201], v[114:117]
	v_mfma_f32_16x16x32_bf16 v[106:109], v[152:155], v[206:209], v[106:109]
	v_mfma_f32_16x16x32_bf16 v[98:101], v[168:171], v[206:209], v[98:101]
	v_mfma_f32_16x16x32_bf16 v[90:93], v[152:155], v[214:217], v[90:93]
	v_mfma_f32_16x16x32_bf16 v[82:85], v[168:171], v[214:217], v[82:85]
	v_mfma_f32_16x16x32_bf16 v[74:77], v[152:155], v[222:225], v[74:77]
	v_mfma_f32_16x16x32_bf16 v[66:69], v[168:171], v[222:225], v[66:69]
	v_mfma_f32_16x16x32_bf16 v[122:125], v[156:159], v[202:205], v[122:125]
	v_mfma_f32_16x16x32_bf16 v[114:117], v[172:175], v[202:205], v[114:117]
	v_mfma_f32_16x16x32_bf16 v[106:109], v[156:159], v[210:213], v[106:109]
	v_mfma_f32_16x16x32_bf16 v[98:101], v[172:175], v[210:213], v[98:101]
	v_mfma_f32_16x16x32_bf16 v[90:93], v[156:159], v[218:221], v[90:93]
	v_mfma_f32_16x16x32_bf16 v[82:85], v[172:175], v[218:221], v[82:85]
	v_mfma_f32_16x16x32_bf16 v[74:77], v[156:159], v[226:229], v[74:77]
	v_mfma_f32_16x16x32_bf16 v[66:69], v[172:175], v[226:229], v[66:69]
	v_mfma_f32_16x16x32_bf16 v[126:129], v[176:179], v[198:201], v[126:129]
	v_mfma_f32_16x16x32_bf16 v[118:121], v[184:187], v[198:201], v[118:121]
	v_mfma_f32_16x16x32_bf16 v[110:113], v[176:179], v[206:209], v[110:113]
	v_mfma_f32_16x16x32_bf16 v[102:105], v[184:187], v[206:209], v[102:105]
	v_mfma_f32_16x16x32_bf16 v[94:97], v[176:179], v[214:217], v[94:97]
	v_mfma_f32_16x16x32_bf16 v[86:89], v[184:187], v[214:217], v[86:89]
	v_mfma_f32_16x16x32_bf16 v[78:81], v[176:179], v[222:225], v[78:81]
	v_mfma_f32_16x16x32_bf16 v[70:73], v[184:187], v[222:225], v[70:73]
	v_mfma_f32_16x16x32_bf16 v[126:129], v[180:183], v[202:205], v[126:129]
	v_mfma_f32_16x16x32_bf16 v[118:121], v[188:191], v[202:205], v[118:121]
	v_mfma_f32_16x16x32_bf16 v[110:113], v[180:183], v[210:213], v[110:113]
	v_mfma_f32_16x16x32_bf16 v[102:105], v[188:191], v[210:213], v[102:105]
	v_mfma_f32_16x16x32_bf16 v[94:97], v[180:183], v[218:221], v[94:97]
	v_mfma_f32_16x16x32_bf16 v[86:89], v[188:191], v[218:221], v[86:89]
	v_mfma_f32_16x16x32_bf16 v[78:81], v[180:183], v[226:229], v[78:81]
	v_mfma_f32_16x16x32_bf16 v[70:73], v[188:191], v[226:229], v[70:73]
	s_barrier
	s_add_u32 s98, s28, 0x80
	s_addc_u32 s99, s29, 0
	s_add_i32 s34, s59, s38
	s_mov_b32 m0, s34
	ds_read_b128 v[198:201], v166 offset:49152
	ds_read_b128 v[202:205], v166 offset:50176
	ds_read_b128 v[206:209], v166 offset:51200
	ds_read_b128 v[210:213], v166 offset:52224
	ds_read_b128 v[214:217], v166 offset:53248
	ds_read_b128 v[218:221], v166 offset:54272
	ds_read_b128 v[222:225], v166 offset:55296
	ds_read_b128 v[226:229], v166 offset:56320
	global_load_lds_dwordx4 v134, s[98:99]
	s_add_i32 m0, s34, 0x2000
	s_add_u32 s28, s28, 0x80080
	s_addc_u32 s29, s29, 0
	s_add_i32 s34, s60, s38
	global_load_lds_dwordx4 v130, s[98:99]
	s_mov_b32 m0, s34
	s_nop 0
	global_load_lds_dwordx4 v134, s[28:29]
	s_add_i32 m0, s34, 0x2000
	s_nop 0
	global_load_lds_dwordx4 v130, s[28:29]
	s_mov_b32 m0, s48
	s_nop 0
	global_load_lds_dwordx4 v136, s[100:101]
	s_mov_b32 m0, s49
	s_nop 0
	global_load_lds_dwordx4 v132, s[100:101]
	s_waitcnt vmcnt(8)
	s_waitcnt lgkmcnt(0)
	s_barrier
	s_waitcnt lgkmcnt(0)
	v_mfma_f32_16x16x32_bf16 v[58:61], v[152:155], v[198:201], v[58:61]
	v_mfma_f32_16x16x32_bf16 v[50:53], v[168:171], v[198:201], v[50:53]
	v_mfma_f32_16x16x32_bf16 v[42:45], v[152:155], v[206:209], v[42:45]
	v_mfma_f32_16x16x32_bf16 v[34:37], v[168:171], v[206:209], v[34:37]
	v_mfma_f32_16x16x32_bf16 v[26:29], v[152:155], v[214:217], v[26:29]
	v_mfma_f32_16x16x32_bf16 v[18:21], v[168:171], v[214:217], v[18:21]
	v_mfma_f32_16x16x32_bf16 v[10:13], v[152:155], v[222:225], v[10:13]
	v_mfma_f32_16x16x32_bf16 v[6:9], v[168:171], v[222:225], v[6:9]
	v_mfma_f32_16x16x32_bf16 v[58:61], v[156:159], v[202:205], v[58:61]
	v_mfma_f32_16x16x32_bf16 v[50:53], v[172:175], v[202:205], v[50:53]
	v_mfma_f32_16x16x32_bf16 v[42:45], v[156:159], v[210:213], v[42:45]
	v_mfma_f32_16x16x32_bf16 v[34:37], v[172:175], v[210:213], v[34:37]
	v_mfma_f32_16x16x32_bf16 v[26:29], v[156:159], v[218:221], v[26:29]
	v_mfma_f32_16x16x32_bf16 v[18:21], v[172:175], v[218:221], v[18:21]
	v_mfma_f32_16x16x32_bf16 v[10:13], v[156:159], v[226:229], v[10:13]
	v_mfma_f32_16x16x32_bf16 v[6:9], v[172:175], v[226:229], v[6:9]
	v_mfma_f32_16x16x32_bf16 v[62:65], v[176:179], v[198:201], v[62:65]
	v_mfma_f32_16x16x32_bf16 v[54:57], v[184:187], v[198:201], v[54:57]
	v_mfma_f32_16x16x32_bf16 v[46:49], v[176:179], v[206:209], v[46:49]
	v_mfma_f32_16x16x32_bf16 v[38:41], v[184:187], v[206:209], v[38:41]
	v_mfma_f32_16x16x32_bf16 v[30:33], v[176:179], v[214:217], v[30:33]
	v_mfma_f32_16x16x32_bf16 v[22:25], v[184:187], v[214:217], v[22:25]
	v_mfma_f32_16x16x32_bf16 v[14:17], v[176:179], v[222:225], v[14:17]
	v_mfma_f32_16x16x32_bf16 v[2:5], v[184:187], v[222:225], v[2:5]
	v_mfma_f32_16x16x32_bf16 v[62:65], v[180:183], v[202:205], v[62:65]
	v_mfma_f32_16x16x32_bf16 v[54:57], v[188:191], v[202:205], v[54:57]
	v_mfma_f32_16x16x32_bf16 v[46:49], v[180:183], v[210:213], v[46:49]
	v_mfma_f32_16x16x32_bf16 v[38:41], v[188:191], v[210:213], v[38:41]
	v_mfma_f32_16x16x32_bf16 v[30:33], v[180:183], v[218:221], v[30:33]
	v_mfma_f32_16x16x32_bf16 v[22:25], v[188:191], v[218:221], v[22:25]
	v_mfma_f32_16x16x32_bf16 v[14:17], v[180:183], v[226:229], v[14:17]
	v_mfma_f32_16x16x32_bf16 v[2:5], v[188:191], v[226:229], v[2:5]
	s_barrier
	s_add_i32 s57, s57, 2
	s_add_i32 s58, s58, 0x400000
	s_cmp_gt_u32 s57, 29
	s_mov_b64 s[28:29], s[30:31]
	.p2align 6

; #define PG8_STAGE(bufoff, gbase, voff) do { _Pragma("unroll") for (int _i = 0; _i < 2; ++_i) \
;         __builtin_amdgcn_global_load_lds((const unsigned*)((const char*)(gbase) + (voff)[_i]), (LAS unsigned*)(lds + (bufoff) + ldsw + _i * 8192), 16, 0, 0); } while (0)
; #define PG8_LDA(dst, b, h) do { _Pragma("unroll") for (int m = 0; m < 4; ++m) _Pragma("unroll") for (int k = 0; k < 2; ++k) dst[m][k] = *(const LAS bf16x8*)(lds + PG8_SA(b, h) + aoff + m * 2048 + k * 1024); } while (0)
; #define PG8_LDB(dst, b, h) do { _Pragma("unroll") for (int n = 0; n < 2; ++n) _Pragma("unroll") for (int k = 0; k < 2; ++k) dst[n][k] = *(const LAS bf16x8*)(lds + PG8_SB(b, h) + boff + n * 2048 + k * 1024); } while (0)
; #define PG8_WAIT_V(n) asm volatile("s_waitcnt vmcnt(" #n ")" ::: "memory")
; #define PG8_WAIT_L(n) asm volatile("s_waitcnt lgkmcnt(" #n ")" ::: "memory")
; #define PG8_BAR __builtin_amdgcn_s_barrier()
; template <class Epi, class Sched, int KC, bool ALIGN_EPI = false, bool SP2 = false, bool ATILED = false>
; __device__ __forceinline__ void gemm_phase(LAS unsigned char* lds, const Gemm g, const Sched& S, const Epi& E, int wave_s) {
;     ...
;         const bool has_next = S.next(ui + 1, nxt);
;         const char* nA = has_next ? (const char*)g.A + (size_t)nxt.pm * tstepA : cA; const char* nB = has_next ? (const char*)g.Bt + (size_t)nxt.pn * tstep : cB;
;         for (int t = 0; t < nt; t += 2) {
;             const bool last = (t == nt - 2);
;             const char* a1 = cA + PG8_AOFF(t + 1);
;             const char* a2 = last ? nA : cA + PG8_AOFF(t + 2); const char* b2 = last ? nB : cB + (size_t)(t + 2) * kstep;
;             const char* a3 = a2 + kstep; const char* b3 = b2 + kstep;
;             if (last && has_next) S.a_ready(nxt);
;             if constexpr (SP2) {
;             PG8_LDB(B0, 0, 0); PG8_LDB(B1, 0, 1); PG8_SCHED; PG8_LDA(At, 0, 0); PG8_STAGE(PG8_SA(1, 1), a1 + hstepA, voffA);
;             PG8_WAIT_V(8); PG8_WAIT_L(0); PG8_BAR; PG8_MMA(0, 0, At, B0); PG8_MMA(0, 1, At, B1); PG8_BAR; PG8_SCHED;
;     ...
; #pragma unroll
;         for (int a = 0; a < 2; ++a)
; #pragma unroll
;             for (int b = 0; b < 2; ++b)
; #pragma unroll
;                 for (int m = 0; m < 4; ++m)
; #pragma unroll
;                     for (int n = 0; n < 2; ++n) acc[a][b][m][n] = (f32x4){0.f, 0.f, 0.f, 0.f};
;         cur = nxt; cA = nA; cB = nB; ++ui;
.LBB0_317:
	s_add_u32 s50, s22, 0x100
	v_mov_b32_e32 v2, 0
	s_addc_u32 s51, s23, 0
	s_mov_b32 s52, -2
	v_mov_b32_e32 v3, v2
	v_mov_b32_e32 v4, v2
	v_mov_b32_e32 v5, v2
	v_mov_b32_e32 v6, v2
	v_mov_b32_e32 v7, v2
	v_mov_b32_e32 v8, v2
	v_mov_b32_e32 v9, v2
	v_mov_b32_e32 v18, v2
	v_mov_b32_e32 v19, v2
	v_mov_b32_e32 v20, v2
	v_mov_b32_e32 v21, v2
	v_mov_b32_e32 v22, v2
	v_mov_b32_e32 v23, v2
	v_mov_b32_e32 v24, v2
	v_mov_b32_e32 v25, v2
	v_mov_b32_e32 v34, v2
	v_mov_b32_e32 v35, v2
	v_mov_b32_e32 v36, v2
	v_mov_b32_e32 v37, v2
	v_mov_b32_e32 v38, v2
	v_mov_b32_e32 v39, v2
	v_mov_b32_e32 v40, v2
	v_mov_b32_e32 v41, v2
	v_mov_b32_e32 v50, v2
	v_mov_b32_e32 v51, v2
	v_mov_b32_e32 v52, v2
	v_mov_b32_e32 v53, v2
	v_mov_b32_e32 v54, v2
	v_mov_b32_e32 v55, v2
	v_mov_b32_e32 v56, v2
	v_mov_b32_e32 v57, v2
	v_mov_b32_e32 v10, v2
	v_mov_b32_e32 v11, v2
	v_mov_b32_e32 v12, v2
	v_mov_b32_e32 v13, v2
	v_mov_b32_e32 v14, v2
	v_mov_b32_e32 v15, v2
	v_mov_b32_e32 v16, v2
	v_mov_b32_e32 v17, v2
	v_mov_b32_e32 v26, v2
	v_mov_b32_e32 v27, v2
	v_mov_b32_e32 v28, v2
	v_mov_b32_e32 v29, v2
	v_mov_b32_e32 v30, v2
	v_mov_b32_e32 v31, v2
	v_mov_b32_e32 v32, v2
	v_mov_b32_e32 v33, v2
	v_mov_b32_e32 v42, v2
	v_mov_b32_e32 v43, v2
	v_mov_b32_e32 v44, v2
	v_mov_b32_e32 v45, v2
	v_mov_b32_e32 v46, v2
	v_mov_b32_e32 v47, v2
	v_mov_b32_e32 v48, v2
	v_mov_b32_e32 v49, v2
	v_mov_b32_e32 v58, v2
	v_mov_b32_e32 v59, v2
	v_mov_b32_e32 v60, v2
	v_mov_b32_e32 v61, v2
	v_mov_b32_e32 v62, v2
	v_mov_b32_e32 v63, v2
	v_mov_b32_e32 v64, v2
	v_mov_b32_e32 v65, v2
	v_mov_b32_e32 v66, v2
	v_mov_b32_e32 v67, v2
	v_mov_b32_e32 v68, v2
	v_mov_b32_e32 v69, v2
	v_mov_b32_e32 v70, v2
	v_mov_b32_e32 v71, v2
	v_mov_b32_e32 v72, v2
	v_mov_b32_e32 v73, v2
	v_mov_b32_e32 v86, v2
	v_mov_b32_e32 v87, v2
	v_mov_b32_e32 v88, v2
	v_mov_b32_e32 v89, v2
	v_mov_b32_e32 v90, v2
	v_mov_b32_e32 v91, v2
	v_mov_b32_e32 v92, v2
	v_mov_b32_e32 v93, v2
	v_mov_b32_e32 v110, v2
	v_mov_b32_e32 v111, v2
	v_mov_b32_e32 v112, v2
	v_mov_b32_e32 v113, v2
	v_mov_b32_e32 v118, v2
	v_mov_b32_e32 v119, v2
	v_mov_b32_e32 v120, v2
	v_mov_b32_e32 v121, v2
	v_mov_b32_e32 v138, v2
	v_mov_b32_e32 v139, v2
	v_mov_b32_e32 v140, v2
	v_mov_b32_e32 v141, v2
	v_mov_b32_e32 v142, v2
	v_mov_b32_e32 v143, v2
	v_mov_b32_e32 v144, v2
	v_mov_b32_e32 v145, v2
	v_mov_b32_e32 v74, v2
	v_mov_b32_e32 v75, v2
	v_mov_b32_e32 v76, v2
	v_mov_b32_e32 v77, v2
	v_mov_b32_e32 v78, v2
	v_mov_b32_e32 v79, v2
	v_mov_b32_e32 v80, v2
	v_mov_b32_e32 v81, v2
	v_mov_b32_e32 v98, v2
	v_mov_b32_e32 v99, v2
	v_mov_b32_e32 v100, v2
	v_mov_b32_e32 v101, v2
	v_mov_b32_e32 v102, v2
	v_mov_b32_e32 v103, v2
	v_mov_b32_e32 v104, v2
	v_mov_b32_e32 v105, v2
	v_mov_b32_e32 v122, v2
	v_mov_b32_e32 v123, v2
	v_mov_b32_e32 v124, v2
	v_mov_b32_e32 v125, v2
	v_mov_b32_e32 v126, v2
	v_mov_b32_e32 v127, v2
	v_mov_b32_e32 v128, v2
	v_mov_b32_e32 v129, v2
	v_mov_b32_e32 v158, v2
	v_mov_b32_e32 v159, v2
	v_mov_b32_e32 v160, v2
	v_mov_b32_e32 v161, v2
	v_mov_b32_e32 v162, v2
	v_mov_b32_e32 v163, v2
	v_mov_b32_e32 v164, v2
	v_mov_b32_e32 v165, v2
	s_add_u32 s8, s20, 0x100
	s_addc_u32 s9, s21, 0
	s_add_i32 s53, 0, 0x10000
	s_cmpk_eq_i32 s52, 0x54
	s_cselect_b32 s25, s17, s9
	s_cselect_b32 s24, s16, s8
	s_cselect_b32 s23, s11, s51
	s_cselect_b32 s22, s10, s50
	s_add_i32 s54, 0, 0x14000
	v_add_u32_e32 v114, s53, v249
	v_add_u32_e32 v150, s54, v249
	ds_read_b128 v[82:85], v114
	ds_read_b128 v[94:97], v114 offset:1024
	ds_read_b128 v[106:109], v114 offset:2048
	ds_read_b128 v[114:117], v114 offset:3072
	ds_read_b128 v[130:133], v150
	ds_read_b128 v[134:137], v150 offset:1024
	ds_read_b128 v[146:149], v150 offset:2048
	ds_read_b128 v[150:153], v150 offset:3072
	s_add_i32 m0, s36, 0xc000
	ds_read_b128 v[154:157], v251
	ds_read_b128 v[166:169], v251 offset:1024
	ds_read_b128 v[170:173], v251 offset:2048
	ds_read_b128 v[174:177], v251 offset:3072
	ds_read_b128 v[178:181], v251 offset:4096
	ds_read_b128 v[182:185], v251 offset:5120
	ds_read_b128 v[186:189], v251 offset:6144
	ds_read_b128 v[194:197], v251 offset:7168
	global_load_lds_dwordx4 v204, s[20:21]
	s_add_i32 m0, s36, 0xe000
	s_nop 0
	global_load_lds_dwordx4 v202, s[20:21]
	s_waitcnt vmcnt(32)
	s_waitcnt lgkmcnt(0)
	s_barrier
	s_waitcnt lgkmcnt(0)
	v_mfma_f32_16x16x32_bf16 v[162:165], v[82:85], v[154:157], v[162:165]
	v_mfma_f32_16x16x32_bf16 v[158:161], v[106:109], v[154:157], v[158:161]
	v_mfma_f32_16x16x32_bf16 v[126:129], v[82:85], v[170:173], v[126:129]
	v_mfma_f32_16x16x32_bf16 v[122:125], v[106:109], v[170:173], v[122:125]
	v_mfma_f32_16x16x32_bf16 v[102:105], v[82:85], v[178:181], v[102:105]
	v_mfma_f32_16x16x32_bf16 v[98:101], v[106:109], v[178:181], v[98:101]
	v_mfma_f32_16x16x32_bf16 v[78:81], v[82:85], v[186:189], v[78:81]
	v_mfma_f32_16x16x32_bf16 v[74:77], v[106:109], v[186:189], v[74:77]
	v_mfma_f32_16x16x32_bf16 v[162:165], v[94:97], v[166:169], v[162:165]
	v_mfma_f32_16x16x32_bf16 v[158:161], v[114:117], v[166:169], v[158:161]
	v_mfma_f32_16x16x32_bf16 v[126:129], v[94:97], v[174:177], v[126:129]
	v_mfma_f32_16x16x32_bf16 v[122:125], v[114:117], v[174:177], v[122:125]
	v_mfma_f32_16x16x32_bf16 v[102:105], v[94:97], v[182:185], v[102:105]
	v_mfma_f32_16x16x32_bf16 v[98:101], v[114:117], v[182:185], v[98:101]
	v_mfma_f32_16x16x32_bf16 v[78:81], v[94:97], v[194:197], v[78:81]
	v_mfma_f32_16x16x32_bf16 v[74:77], v[114:117], v[194:197], v[74:77]
	v_mfma_f32_16x16x32_bf16 v[142:145], v[130:133], v[154:157], v[142:145]
	v_mfma_f32_16x16x32_bf16 v[138:141], v[146:149], v[154:157], v[138:141]
	v_mfma_f32_16x16x32_bf16 v[118:121], v[130:133], v[170:173], v[118:121]
	v_mfma_f32_16x16x32_bf16 v[110:113], v[146:149], v[170:173], v[110:113]
	v_mfma_f32_16x16x32_bf16 v[90:93], v[130:133], v[178:181], v[90:93]
	v_mfma_f32_16x16x32_bf16 v[86:89], v[146:149], v[178:181], v[86:89]
	v_mfma_f32_16x16x32_bf16 v[70:73], v[130:133], v[186:189], v[70:73]
	v_mfma_f32_16x16x32_bf16 v[66:69], v[146:149], v[186:189], v[66:69]
	v_mfma_f32_16x16x32_bf16 v[142:145], v[134:137], v[166:169], v[142:145]
	v_mfma_f32_16x16x32_bf16 v[138:141], v[150:153], v[166:169], v[138:141]
	v_mfma_f32_16x16x32_bf16 v[118:121], v[134:137], v[174:177], v[118:121]
	v_mfma_f32_16x16x32_bf16 v[110:113], v[150:153], v[174:177], v[110:113]
	v_mfma_f32_16x16x32_bf16 v[90:93], v[134:137], v[182:185], v[90:93]
	v_mfma_f32_16x16x32_bf16 v[86:89], v[150:153], v[182:185], v[86:89]
	v_mfma_f32_16x16x32_bf16 v[70:73], v[134:137], v[194:197], v[70:73]
	v_mfma_f32_16x16x32_bf16 v[66:69], v[150:153], v[194:197], v[66:69]
	s_barrier
; #define PG8_STAGE(bufoff, gbase, voff) do { _Pragma("unroll") for (int _i = 0; _i < 2; ++_i) \
;         __builtin_amdgcn_global_load_lds((const unsigned*)((const char*)(gbase) + (voff)[_i]), (LAS unsigned*)(lds + (bufoff) + ldsw + _i * 8192), 16, 0, 0); } while (0)
; #define PG8_LDA(dst, b, h) do { _Pragma("unroll") for (int m = 0; m < 4; ++m) _Pragma("unroll") for (int k = 0; k < 2; ++k) dst[m][k] = *(const LAS bf16x8*)(lds + PG8_SA(b, h) + aoff + m * 2048 + k * 1024); } while (0)
; #define PG8_LDB(dst, b, h) do { _Pragma("unroll") for (int n = 0; n < 2; ++n) _Pragma("unroll") for (int k = 0; k < 2; ++k) dst[n][k] = *(const LAS bf16x8*)(lds + PG8_SB(b, h) + boff + n * 2048 + k * 1024); } while (0)
; #define PG8_MMA(ai, bj, At, Bt) do { __builtin_amdgcn_s_setprio(1); _Pragma("unroll") for (int m = 0; m < 4; ++m) _Pragma("unroll") for (int n = 0; n < 2; ++n) _Pragma("unroll") for (int k = 0; k < 2; ++k) \
;         acc[ai][bj][m][n] = __builtin_amdgcn_mfma_f32_16x16x32_bf16(Bt[n][k], At[m][k], acc[ai][bj][m][n], 0, 0, 0); __builtin_amdgcn_s_setprio(0); } while (0)
; #define PG8_WAIT_V(n) asm volatile("s_waitcnt vmcnt(" #n ")" ::: "memory")
; #define PG8_WAIT_L(n) asm volatile("s_waitcnt lgkmcnt(" #n ")" ::: "memory")
; #define PG8_BAR __builtin_amdgcn_s_barrier()
; #define PG8_SCHED __builtin_amdgcn_sched_barrier(0)
; template <class Epi, class Sched, int KC, bool ALIGN_EPI = false, bool SP2 = false, bool ATILED = false>
; __device__ __forceinline__ void gemm_phase(LAS unsigned char* lds, const Gemm g, const Sched& S, const Epi& E, int wave_s) {
;     ...
;             PG8_LDA(At, 0, 1); PG8_STAGE(PG8_SB(0, 0), b2, voffB); PG8_STAGE(PG8_SB(0, 1), b2 + hstepB, voffB); PG8_STAGE(PG8_SA(0, 0), a2, voffA);
;             PG8_WAIT_V(8); PG8_WAIT_L(0); PG8_BAR; PG8_MMA(1, 0, At, B0); PG8_MMA(1, 1, At, B1); PG8_BAR; PG8_SCHED;
;             PG8_LDB(B0, 1, 0); PG8_LDB(B1, 1, 1); PG8_SCHED; PG8_LDA(At, 1, 0); PG8_STAGE(PG8_SA(0, 1), a2 + hstepA, voffA);
;             PG8_WAIT_V(8); PG8_WAIT_L(0); PG8_BAR; PG8_MMA(0, 0, At, B0); PG8_MMA(0, 1, At, B1); PG8_BAR; PG8_SCHED;
	s_add_i32 s20, s53, s35
	s_mov_b32 m0, s20
	ds_read_b128 v[154:157], v251 offset:16384
	ds_read_b128 v[166:169], v251 offset:17408
	ds_read_b128 v[170:173], v251 offset:18432
	ds_read_b128 v[174:177], v251 offset:19456
	ds_read_b128 v[178:181], v251 offset:20480
	ds_read_b128 v[182:185], v251 offset:21504
	ds_read_b128 v[186:189], v251 offset:22528
	ds_read_b128 v[194:197], v251 offset:23552
	global_load_lds_dwordx4 v0, s[22:23]
	s_add_i32 m0, s20, 0x2000
	s_add_u32 s20, s22, 0x58000
	s_addc_u32 s21, s23, 0
	s_add_i32 s53, s54, s35
	global_load_lds_dwordx4 v198, s[22:23]
	s_mov_b32 m0, s53
	s_nop 0
	global_load_lds_dwordx4 v0, s[20:21]
	s_add_i32 m0, s53, 0x2000
	s_nop 0
	global_load_lds_dwordx4 v198, s[20:21]
	s_mov_b32 m0, s36
	s_nop 0
	global_load_lds_dwordx4 v190, s[24:25]
	s_mov_b32 m0, s37
	s_nop 0
	global_load_lds_dwordx4 v192, s[24:25]
	s_waitcnt vmcnt(32)
	s_waitcnt lgkmcnt(0)
	s_barrier
	s_waitcnt lgkmcnt(0)
	v_mfma_f32_16x16x32_bf16 v[62:65], v[82:85], v[154:157], v[62:65]
	v_mfma_f32_16x16x32_bf16 v[58:61], v[106:109], v[154:157], v[58:61]
	v_mfma_f32_16x16x32_bf16 v[46:49], v[82:85], v[170:173], v[46:49]
	v_mfma_f32_16x16x32_bf16 v[42:45], v[106:109], v[170:173], v[42:45]
	v_mfma_f32_16x16x32_bf16 v[30:33], v[82:85], v[178:181], v[30:33]
	v_mfma_f32_16x16x32_bf16 v[26:29], v[106:109], v[178:181], v[26:29]
	v_mfma_f32_16x16x32_bf16 v[14:17], v[82:85], v[186:189], v[14:17]
	v_mfma_f32_16x16x32_bf16 v[10:13], v[106:109], v[186:189], v[10:13]
	v_mfma_f32_16x16x32_bf16 v[62:65], v[94:97], v[166:169], v[62:65]
	v_mfma_f32_16x16x32_bf16 v[58:61], v[114:117], v[166:169], v[58:61]
	v_mfma_f32_16x16x32_bf16 v[46:49], v[94:97], v[174:177], v[46:49]
	v_mfma_f32_16x16x32_bf16 v[42:45], v[114:117], v[174:177], v[42:45]
	v_mfma_f32_16x16x32_bf16 v[30:33], v[94:97], v[182:185], v[30:33]
	v_mfma_f32_16x16x32_bf16 v[26:29], v[114:117], v[182:185], v[26:29]
	v_mfma_f32_16x16x32_bf16 v[14:17], v[94:97], v[194:197], v[14:17]
	v_mfma_f32_16x16x32_bf16 v[10:13], v[114:117], v[194:197], v[10:13]
	v_mfma_f32_16x16x32_bf16 v[54:57], v[130:133], v[154:157], v[54:57]
	v_mfma_f32_16x16x32_bf16 v[50:53], v[146:149], v[154:157], v[50:53]
	v_mfma_f32_16x16x32_bf16 v[38:41], v[130:133], v[170:173], v[38:41]
	v_mfma_f32_16x16x32_bf16 v[34:37], v[146:149], v[170:173], v[34:37]
	v_mfma_f32_16x16x32_bf16 v[22:25], v[130:133], v[178:181], v[22:25]
	v_mfma_f32_16x16x32_bf16 v[18:21], v[146:149], v[178:181], v[18:21]
	v_mfma_f32_16x16x32_bf16 v[6:9], v[130:133], v[186:189], v[6:9]
	v_mfma_f32_16x16x32_bf16 v[2:5], v[146:149], v[186:189], v[2:5]
	v_mfma_f32_16x16x32_bf16 v[54:57], v[134:137], v[166:169], v[54:57]
	v_mfma_f32_16x16x32_bf16 v[50:53], v[150:153], v[166:169], v[50:53]
	v_mfma_f32_16x16x32_bf16 v[38:41], v[134:137], v[174:177], v[38:41]
	v_mfma_f32_16x16x32_bf16 v[34:37], v[150:153], v[174:177], v[34:37]
	v_mfma_f32_16x16x32_bf16 v[22:25], v[134:137], v[182:185], v[22:25]
	v_mfma_f32_16x16x32_bf16 v[18:21], v[150:153], v[182:185], v[18:21]
	v_mfma_f32_16x16x32_bf16 v[6:9], v[134:137], v[194:197], v[6:9]
	v_mfma_f32_16x16x32_bf16 v[2:5], v[150:153], v[194:197], v[2:5]
	s_barrier
	s_add_i32 s53, 0, 0x18000
	s_add_i32 s54, 0, 0x1c000
	v_add_u32_e32 v114, s53, v249
	v_add_u32_e32 v150, s54, v249
	ds_read_b128 v[82:85], v114
	ds_read_b128 v[94:97], v114 offset:1024
	ds_read_b128 v[106:109], v114 offset:2048
	ds_read_b128 v[114:117], v114 offset:3072
	ds_read_b128 v[130:133], v150
	ds_read_b128 v[134:137], v150 offset:1024
	ds_read_b128 v[146:149], v150 offset:2048
	ds_read_b128 v[150:153], v150 offset:3072
	s_add_u32 s20, s24, 0x160000
	s_addc_u32 s21, s25, 0
	s_mov_b32 m0, s38
	ds_read_b128 v[154:157], v251 offset:32768
	ds_read_b128 v[166:169], v251 offset:33792
	ds_read_b128 v[170:173], v251 offset:34816
	ds_read_b128 v[174:177], v251 offset:35840
	ds_read_b128 v[178:181], v251 offset:36864
	ds_read_b128 v[182:185], v251 offset:37888
	ds_read_b128 v[186:189], v251 offset:38912
	ds_read_b128 v[194:197], v251 offset:39936
	global_load_lds_dwordx4 v190, s[20:21]
	s_mov_b32 m0, s39
	s_nop 0
	global_load_lds_dwordx4 v192, s[20:21]
	s_waitcnt vmcnt(8)
	s_waitcnt lgkmcnt(0)
	s_barrier
; #define PG8_STAGE(bufoff, gbase, voff) do { _Pragma("unroll") for (int _i = 0; _i < 2; ++_i) \
;         __builtin_amdgcn_global_load_lds((const unsigned*)((const char*)(gbase) + (voff)[_i]), (LAS unsigned*)(lds + (bufoff) + ldsw + _i * 8192), 16, 0, 0); } while (0)
; #define PG8_LDA(dst, b, h) do { _Pragma("unroll") for (int m = 0; m < 4; ++m) _Pragma("unroll") for (int k = 0; k < 2; ++k) dst[m][k] = *(const LAS bf16x8*)(lds + PG8_SA(b, h) + aoff + m * 2048 + k * 1024); } while (0)
; #define PG8_LDB(dst, b, h) do { _Pragma("unroll") for (int n = 0; n < 2; ++n) _Pragma("unroll") for (int k = 0; k < 2; ++k) dst[n][k] = *(const LAS bf16x8*)(lds + PG8_SB(b, h) + boff + n * 2048 + k * 1024); } while (0)
; #define PG8_MMA(ai, bj, At, Bt) do { __builtin_amdgcn_s_setprio(1); _Pragma("unroll") for (int m = 0; m < 4; ++m) _Pragma("unroll") for (int n = 0; n < 2; ++n) _Pragma("unroll") for (int k = 0; k < 2; ++k) \
;         acc[ai][bj][m][n] = __builtin_amdgcn_mfma_f32_16x16x32_bf16(Bt[n][k], At[m][k], acc[ai][bj][m][n], 0, 0, 0); __builtin_amdgcn_s_setprio(0); } while (0)
; #define PG8_WAIT_V(n) asm volatile("s_waitcnt vmcnt(" #n ")" ::: "memory")
; #define PG8_WAIT_L(n) asm volatile("s_waitcnt lgkmcnt(" #n ")" ::: "memory")
; #define PG8_BAR __builtin_amdgcn_s_barrier()
; #define PG8_SCHED __builtin_amdgcn_sched_barrier(0)
; template <class Epi, class Sched, int KC, bool ALIGN_EPI = false, bool SP2 = false, bool ATILED = false>
; __device__ __forceinline__ void gemm_phase(LAS unsigned char* lds, const Gemm g, const Sched& S, const Epi& E, int wave_s) {
;     ...
;             PG8_LDB(B0, 1, 0); PG8_LDB(B1, 1, 1); PG8_SCHED; PG8_LDA(At, 1, 0); PG8_STAGE(PG8_SA(0, 1), a2 + hstepA, voffA);
;             PG8_WAIT_V(8); PG8_WAIT_L(0); PG8_BAR; PG8_MMA(0, 0, At, B0); PG8_MMA(0, 1, At, B1); PG8_BAR; PG8_SCHED;
;             PG8_LDA(At, 1, 1); PG8_STAGE(PG8_SB(1, 0), b3, voffB); PG8_STAGE(PG8_SB(1, 1), b3 + hstepB, voffB); PG8_STAGE(PG8_SA(1, 0), a3, voffA);
;             PG8_WAIT_V(8); PG8_WAIT_L(0); PG8_BAR; PG8_MMA(1, 0, At, B0); PG8_MMA(1, 1, At, B1); PG8_BAR; PG8_SCHED;
	s_waitcnt lgkmcnt(0)
	v_mfma_f32_16x16x32_bf16 v[162:165], v[82:85], v[154:157], v[162:165]
	v_mfma_f32_16x16x32_bf16 v[158:161], v[106:109], v[154:157], v[158:161]
	v_mfma_f32_16x16x32_bf16 v[126:129], v[82:85], v[170:173], v[126:129]
	v_mfma_f32_16x16x32_bf16 v[122:125], v[106:109], v[170:173], v[122:125]
	v_mfma_f32_16x16x32_bf16 v[102:105], v[82:85], v[178:181], v[102:105]
	v_mfma_f32_16x16x32_bf16 v[98:101], v[106:109], v[178:181], v[98:101]
	v_mfma_f32_16x16x32_bf16 v[78:81], v[82:85], v[186:189], v[78:81]
	v_mfma_f32_16x16x32_bf16 v[74:77], v[106:109], v[186:189], v[74:77]
	v_mfma_f32_16x16x32_bf16 v[162:165], v[94:97], v[166:169], v[162:165]
	v_mfma_f32_16x16x32_bf16 v[158:161], v[114:117], v[166:169], v[158:161]
	v_mfma_f32_16x16x32_bf16 v[126:129], v[94:97], v[174:177], v[126:129]
	v_mfma_f32_16x16x32_bf16 v[122:125], v[114:117], v[174:177], v[122:125]
	v_mfma_f32_16x16x32_bf16 v[102:105], v[94:97], v[182:185], v[102:105]
	v_mfma_f32_16x16x32_bf16 v[98:101], v[114:117], v[182:185], v[98:101]
	v_mfma_f32_16x16x32_bf16 v[78:81], v[94:97], v[194:197], v[78:81]
	v_mfma_f32_16x16x32_bf16 v[74:77], v[114:117], v[194:197], v[74:77]
	v_mfma_f32_16x16x32_bf16 v[142:145], v[130:133], v[154:157], v[142:145]
	v_mfma_f32_16x16x32_bf16 v[138:141], v[146:149], v[154:157], v[138:141]
	v_mfma_f32_16x16x32_bf16 v[118:121], v[130:133], v[170:173], v[118:121]
	v_mfma_f32_16x16x32_bf16 v[110:113], v[146:149], v[170:173], v[110:113]
	v_mfma_f32_16x16x32_bf16 v[90:93], v[130:133], v[178:181], v[90:93]
	v_mfma_f32_16x16x32_bf16 v[86:89], v[146:149], v[178:181], v[86:89]
	v_mfma_f32_16x16x32_bf16 v[70:73], v[130:133], v[186:189], v[70:73]
	v_mfma_f32_16x16x32_bf16 v[66:69], v[146:149], v[186:189], v[66:69]
	v_mfma_f32_16x16x32_bf16 v[142:145], v[134:137], v[166:169], v[142:145]
	v_mfma_f32_16x16x32_bf16 v[138:141], v[150:153], v[166:169], v[138:141]
	v_mfma_f32_16x16x32_bf16 v[118:121], v[134:137], v[174:177], v[118:121]
	v_mfma_f32_16x16x32_bf16 v[110:113], v[150:153], v[174:177], v[110:113]
	v_mfma_f32_16x16x32_bf16 v[90:93], v[134:137], v[182:185], v[90:93]
	v_mfma_f32_16x16x32_bf16 v[86:89], v[150:153], v[182:185], v[86:89]
	v_mfma_f32_16x16x32_bf16 v[70:73], v[134:137], v[194:197], v[70:73]
	v_mfma_f32_16x16x32_bf16 v[66:69], v[150:153], v[194:197], v[66:69]
	s_barrier
	s_add_u32 s98, s22, 0x80
	s_addc_u32 s99, s23, 0
	s_add_u32 s100, s24, 0x80
	s_addc_u32 s101, s25, 0
	s_add_i32 s20, s53, s35
	s_mov_b32 m0, s20
	ds_read_b128 v[154:157], v251 offset:49152
	ds_read_b128 v[166:169], v251 offset:50176
	ds_read_b128 v[170:173], v251 offset:51200
	ds_read_b128 v[174:177], v251 offset:52224
	ds_read_b128 v[178:181], v251 offset:53248
	ds_read_b128 v[182:185], v251 offset:54272
	ds_read_b128 v[186:189], v251 offset:55296
	ds_read_b128 v[194:197], v251 offset:56320
	global_load_lds_dwordx4 v0, s[98:99]
	s_add_i32 m0, s20, 0x2000
	s_add_u32 s20, s22, 0x58080
	s_addc_u32 s21, s23, 0
	s_add_i32 s22, s54, s35
	global_load_lds_dwordx4 v198, s[98:99]
	s_mov_b32 m0, s22
	s_nop 0
	global_load_lds_dwordx4 v0, s[20:21]
	s_add_i32 m0, s22, 0x2000
	s_nop 0
	global_load_lds_dwordx4 v198, s[20:21]
	s_mov_b32 m0, s43
	s_nop 0
	global_load_lds_dwordx4 v190, s[100:101]
	s_mov_b32 m0, s44
	s_nop 0
	global_load_lds_dwordx4 v192, s[100:101]
	s_waitcnt vmcnt(8)
	s_waitcnt lgkmcnt(0)
	s_barrier
	s_waitcnt lgkmcnt(0)
	v_mfma_f32_16x16x32_bf16 v[62:65], v[82:85], v[154:157], v[62:65]
	v_mfma_f32_16x16x32_bf16 v[58:61], v[106:109], v[154:157], v[58:61]
	v_mfma_f32_16x16x32_bf16 v[46:49], v[82:85], v[170:173], v[46:49]
	v_mfma_f32_16x16x32_bf16 v[42:45], v[106:109], v[170:173], v[42:45]
	v_mfma_f32_16x16x32_bf16 v[30:33], v[82:85], v[178:181], v[30:33]
	v_mfma_f32_16x16x32_bf16 v[26:29], v[106:109], v[178:181], v[26:29]
	v_mfma_f32_16x16x32_bf16 v[14:17], v[82:85], v[186:189], v[14:17]
	v_mfma_f32_16x16x32_bf16 v[10:13], v[106:109], v[186:189], v[10:13]
	v_mfma_f32_16x16x32_bf16 v[62:65], v[94:97], v[166:169], v[62:65]
	v_mfma_f32_16x16x32_bf16 v[58:61], v[114:117], v[166:169], v[58:61]
	v_mfma_f32_16x16x32_bf16 v[46:49], v[94:97], v[174:177], v[46:49]
	v_mfma_f32_16x16x32_bf16 v[42:45], v[114:117], v[174:177], v[42:45]
	v_mfma_f32_16x16x32_bf16 v[30:33], v[94:97], v[182:185], v[30:33]
	v_mfma_f32_16x16x32_bf16 v[26:29], v[114:117], v[182:185], v[26:29]
	v_mfma_f32_16x16x32_bf16 v[14:17], v[94:97], v[194:197], v[14:17]
	v_mfma_f32_16x16x32_bf16 v[10:13], v[114:117], v[194:197], v[10:13]
	v_mfma_f32_16x16x32_bf16 v[54:57], v[130:133], v[154:157], v[54:57]
	v_mfma_f32_16x16x32_bf16 v[50:53], v[146:149], v[154:157], v[50:53]
	v_mfma_f32_16x16x32_bf16 v[38:41], v[130:133], v[170:173], v[38:41]
	v_mfma_f32_16x16x32_bf16 v[34:37], v[146:149], v[170:173], v[34:37]
	v_mfma_f32_16x16x32_bf16 v[22:25], v[130:133], v[178:181], v[22:25]
	v_mfma_f32_16x16x32_bf16 v[18:21], v[146:149], v[178:181], v[18:21]
	v_mfma_f32_16x16x32_bf16 v[6:9], v[130:133], v[186:189], v[6:9]
	v_mfma_f32_16x16x32_bf16 v[2:5], v[146:149], v[186:189], v[2:5]
	v_mfma_f32_16x16x32_bf16 v[54:57], v[134:137], v[166:169], v[54:57]
	v_mfma_f32_16x16x32_bf16 v[50:53], v[150:153], v[166:169], v[50:53]
	v_mfma_f32_16x16x32_bf16 v[38:41], v[134:137], v[174:177], v[38:41]
	v_mfma_f32_16x16x32_bf16 v[34:37], v[150:153], v[174:177], v[34:37]
	v_mfma_f32_16x16x32_bf16 v[22:25], v[134:137], v[182:185], v[22:25]
	v_mfma_f32_16x16x32_bf16 v[18:21], v[150:153], v[182:185], v[18:21]
	v_mfma_f32_16x16x32_bf16 v[6:9], v[134:137], v[194:197], v[6:9]
	v_mfma_f32_16x16x32_bf16 v[2:5], v[150:153], v[194:197], v[2:5]
	s_barrier
	s_add_i32 s52, s52, 2
	s_add_u32 s50, s50, 0x100
	s_addc_u32 s51, s51, 0
	s_cmpk_gt_u32 s52, 0x55
	s_mov_b64 s[20:21], s[8:9]
	.p2align 6

; #define PG8_STAGE(bufoff, gbase, voff) do { _Pragma("unroll") for (int _i = 0; _i < 2; ++_i) \
;         __builtin_amdgcn_global_load_lds((const unsigned*)((const char*)(gbase) + (voff)[_i]), (LAS unsigned*)(lds + (bufoff) + ldsw + _i * 8192), 16, 0, 0); } while (0)
; #define PG8_LDA(dst, b, h) do { _Pragma("unroll") for (int m = 0; m < 4; ++m) _Pragma("unroll") for (int k = 0; k < 2; ++k) dst[m][k] = *(const LAS bf16x8*)(lds + PG8_SA(b, h) + aoff + m * 2048 + k * 1024); } while (0)
; #define PG8_LDB(dst, b, h) do { _Pragma("unroll") for (int n = 0; n < 2; ++n) _Pragma("unroll") for (int k = 0; k < 2; ++k) dst[n][k] = *(const LAS bf16x8*)(lds + PG8_SB(b, h) + boff + n * 2048 + k * 1024); } while (0)
; #define PG8_WAIT_V(n) asm volatile("s_waitcnt vmcnt(" #n ")" ::: "memory")
; #define PG8_WAIT_L(n) asm volatile("s_waitcnt lgkmcnt(" #n ")" ::: "memory")
; #define PG8_BAR __builtin_amdgcn_s_barrier()
; template <class Epi, class Sched, int KC, bool ALIGN_EPI = false, bool SP2 = false, bool ATILED = false>
; __device__ __forceinline__ void gemm_phase(LAS unsigned char* lds, const Gemm g, const Sched& S, const Epi& E, int wave_s) {
;     ...
;         const bool has_next = S.next(ui + 1, nxt);
;         const char* nA = has_next ? (const char*)g.A + (size_t)nxt.pm * tstepA : cA; const char* nB = has_next ? (const char*)g.Bt + (size_t)nxt.pn * tstep : cB;
;         for (int t = 0; t < nt; t += 2) {
;             const bool last = (t == nt - 2);
;             const char* a1 = cA + PG8_AOFF(t + 1);
;             const char* a2 = last ? nA : cA + PG8_AOFF(t + 2); const char* b2 = last ? nB : cB + (size_t)(t + 2) * kstep;
;             const char* a3 = a2 + kstep; const char* b3 = b2 + kstep;
;             if (last && has_next) S.a_ready(nxt);
;             if constexpr (SP2) {
;             PG8_LDB(B0, 0, 0); PG8_LDB(B1, 0, 1); PG8_SCHED; PG8_LDA(At, 0, 0); PG8_STAGE(PG8_SA(1, 1), a1 + hstepA, voffA);
;             PG8_WAIT_V(8); PG8_WAIT_L(0); PG8_BAR; PG8_MMA(0, 0, At, B0); PG8_MMA(0, 1, At, B1); PG8_BAR; PG8_SCHED;
;     ...
; #pragma unroll
;         for (int a = 0; a < 2; ++a)
; #pragma unroll
;             for (int b = 0; b < 2; ++b)
; #pragma unroll
;                 for (int m = 0; m < 4; ++m)
; #pragma unroll
;                     for (int n = 0; n < 2; ++n) acc[a][b][m][n] = (f32x4){0.f, 0.f, 0.f, 0.f};
;         cur = nxt; cA = nA; cB = nB; ++ui;
.LBB0_429:
	s_ashr_i32 s19, s18, 31
	s_lshl_b64 s[20:21], s[18:19], 17
	s_add_u32 s20, s42, s20
	s_addc_u32 s21, s43, s21
	s_and_b64 s[22:23], s[6:7], exec
	s_cselect_b32 s19, s21, s27
	s_cselect_b32 s61, s20, s26
	s_ashr_i32 s17, s16, 31
	s_lshl_b64 s[22:23], s[16:17], 20
	s_add_u32 s22, s44, s22
	s_addc_u32 s23, s45, s23
	s_and_b64 s[30:31], s[6:7], exec
	s_cselect_b32 s17, s23, s29
	s_cselect_b32 s62, s22, s28
	s_add_u32 s63, s28, 0x100
	v_mov_b32_e32 v2, 0
	s_addc_u32 s64, s29, 0
	s_mov_b32 s65, -2
	s_mov_b64 s[28:29], 0
	s_mov_b32 s66, 0x400000
	v_mov_b32_e32 v3, v2
	v_mov_b32_e32 v4, v2
	v_mov_b32_e32 v5, v2
	v_mov_b32_e32 v6, v2
	v_mov_b32_e32 v7, v2
	v_mov_b32_e32 v8, v2
	v_mov_b32_e32 v9, v2
	v_mov_b32_e32 v14, v2
	v_mov_b32_e32 v15, v2
	v_mov_b32_e32 v16, v2
	v_mov_b32_e32 v17, v2
	v_mov_b32_e32 v22, v2
	v_mov_b32_e32 v23, v2
	v_mov_b32_e32 v24, v2
	v_mov_b32_e32 v25, v2
	v_mov_b32_e32 v30, v2
	v_mov_b32_e32 v31, v2
	v_mov_b32_e32 v32, v2
	v_mov_b32_e32 v33, v2
	v_mov_b32_e32 v38, v2
	v_mov_b32_e32 v39, v2
	v_mov_b32_e32 v40, v2
	v_mov_b32_e32 v41, v2
	v_mov_b32_e32 v46, v2
	v_mov_b32_e32 v47, v2
	v_mov_b32_e32 v48, v2
	v_mov_b32_e32 v49, v2
	v_mov_b32_e32 v54, v2
	v_mov_b32_e32 v55, v2
	v_mov_b32_e32 v56, v2
	v_mov_b32_e32 v57, v2
	v_mov_b32_e32 v10, v2
	v_mov_b32_e32 v11, v2
	v_mov_b32_e32 v12, v2
	v_mov_b32_e32 v13, v2
	v_mov_b32_e32 v18, v2
	v_mov_b32_e32 v19, v2
	v_mov_b32_e32 v20, v2
	v_mov_b32_e32 v21, v2
	v_mov_b32_e32 v26, v2
	v_mov_b32_e32 v27, v2
	v_mov_b32_e32 v28, v2
	v_mov_b32_e32 v29, v2
	v_mov_b32_e32 v34, v2
	v_mov_b32_e32 v35, v2
	v_mov_b32_e32 v36, v2
	v_mov_b32_e32 v37, v2
	v_mov_b32_e32 v42, v2
	v_mov_b32_e32 v43, v2
	v_mov_b32_e32 v44, v2
	v_mov_b32_e32 v45, v2
	v_mov_b32_e32 v50, v2
	v_mov_b32_e32 v51, v2
	v_mov_b32_e32 v52, v2
	v_mov_b32_e32 v53, v2
	v_mov_b32_e32 v58, v2
	v_mov_b32_e32 v59, v2
	v_mov_b32_e32 v60, v2
	v_mov_b32_e32 v61, v2
	v_mov_b32_e32 v62, v2
	v_mov_b32_e32 v63, v2
	v_mov_b32_e32 v64, v2
	v_mov_b32_e32 v65, v2
	v_mov_b32_e32 v66, v2
	v_mov_b32_e32 v67, v2
	v_mov_b32_e32 v68, v2
	v_mov_b32_e32 v69, v2
	v_mov_b32_e32 v70, v2
	v_mov_b32_e32 v71, v2
	v_mov_b32_e32 v72, v2
	v_mov_b32_e32 v73, v2
	v_mov_b32_e32 v78, v2
	v_mov_b32_e32 v79, v2
	v_mov_b32_e32 v80, v2
	v_mov_b32_e32 v81, v2
	v_mov_b32_e32 v86, v2
	v_mov_b32_e32 v87, v2
	v_mov_b32_e32 v88, v2
	v_mov_b32_e32 v89, v2
	v_mov_b32_e32 v94, v2
	v_mov_b32_e32 v95, v2
	v_mov_b32_e32 v96, v2
	v_mov_b32_e32 v97, v2
	v_mov_b32_e32 v102, v2
	v_mov_b32_e32 v103, v2
	v_mov_b32_e32 v104, v2
	v_mov_b32_e32 v105, v2
	v_mov_b32_e32 v110, v2
	v_mov_b32_e32 v111, v2
	v_mov_b32_e32 v112, v2
	v_mov_b32_e32 v113, v2
	v_mov_b32_e32 v118, v2
	v_mov_b32_e32 v119, v2
	v_mov_b32_e32 v120, v2
	v_mov_b32_e32 v121, v2
	v_mov_b32_e32 v74, v2
	v_mov_b32_e32 v75, v2
	v_mov_b32_e32 v76, v2
	v_mov_b32_e32 v77, v2
	v_mov_b32_e32 v82, v2
	v_mov_b32_e32 v83, v2
	v_mov_b32_e32 v84, v2
	v_mov_b32_e32 v85, v2
	v_mov_b32_e32 v90, v2
	v_mov_b32_e32 v91, v2
	v_mov_b32_e32 v92, v2
	v_mov_b32_e32 v93, v2
	v_mov_b32_e32 v98, v2
	v_mov_b32_e32 v99, v2
	v_mov_b32_e32 v100, v2
	v_mov_b32_e32 v101, v2
	v_mov_b32_e32 v106, v2
	v_mov_b32_e32 v107, v2
	v_mov_b32_e32 v108, v2
	v_mov_b32_e32 v109, v2
	v_mov_b32_e32 v114, v2
	v_mov_b32_e32 v115, v2
	v_mov_b32_e32 v116, v2
	v_mov_b32_e32 v117, v2
	v_mov_b32_e32 v122, v2
	v_mov_b32_e32 v123, v2
	v_mov_b32_e32 v124, v2
	v_mov_b32_e32 v125, v2
	v_mov_b32_e32 v126, v2
	v_mov_b32_e32 v127, v2
	v_mov_b32_e32 v128, v2
	v_mov_b32_e32 v129, v2
	s_add_i32 s30, s66, 0xffc00000
	s_and_b32 s30, s30, 0x3800000
	s_and_b32 s31, s28, 0x100
	s_or_b32 s67, s31, s30
	s_and_b32 s34, s66, 0x7800000
	s_add_u32 s30, s28, 0x100
	s_addc_u32 s31, s29, 0
	s_and_b32 s35, s30, 0x100
	s_or_b32 s34, s34, s35
	s_add_u32 s34, s26, s34
	s_addc_u32 s35, s27, 0
	s_add_u32 s28, s63, s28
	s_addc_u32 s29, s64, s29
	s_add_i32 s70, 0, 0x10000
	s_cmp_eq_u32 s65, 28
	s_cselect_b32 s35, s19, s35
	s_cselect_b32 s34, s61, s34
	v_add_u32_e32 v139, s70, v165
	s_cselect_b32 s29, s17, s29
	s_cselect_b32 s28, s62, s28
	s_add_i32 s71, 0, 0x14000
	ds_read_b128 v[152:155], v139
	ds_read_b128 v[160:163], v139 offset:1024
	ds_read_b128 v[174:177], v139 offset:2048
	ds_read_b128 v[178:181], v139 offset:3072
	v_add_u32_e32 v139, s71, v165
	ds_read_b128 v[182:185], v139
	ds_read_b128 v[186:189], v139 offset:1024
	ds_read_b128 v[190:193], v139 offset:2048
	ds_read_b128 v[194:197], v139 offset:3072
	s_add_u32 s67, s26, s67
	s_addc_u32 s69, s27, 0
	s_add_u32 s68, s67, 0x10080
	s_addc_u32 s69, s69, 0
	s_add_i32 m0, s25, 0xc000
	ds_read_b128 v[198:201], v173
	ds_read_b128 v[202:205], v173 offset:1024
	ds_read_b128 v[206:209], v173 offset:2048
	ds_read_b128 v[210:213], v173 offset:3072
	ds_read_b128 v[214:217], v173 offset:4096
	ds_read_b128 v[218:221], v173 offset:5120
	ds_read_b128 v[222:225], v173 offset:6144
	ds_read_b128 v[226:229], v173 offset:7168
	global_load_lds_dwordx4 v136, s[68:69]
	s_add_i32 m0, s25, 0xe000
	s_nop 0
	global_load_lds_dwordx4 v132, s[68:69]
	s_waitcnt vmcnt(24)
	s_waitcnt lgkmcnt(0)
	s_barrier
; #define PG8_STAGE(bufoff, gbase, voff) do { _Pragma("unroll") for (int _i = 0; _i < 2; ++_i) \
;         __builtin_amdgcn_global_load_lds((const unsigned*)((const char*)(gbase) + (voff)[_i]), (LAS unsigned*)(lds + (bufoff) + ldsw + _i * 8192), 16, 0, 0); } while (0)
; #define PG8_LDA(dst, b, h) do { _Pragma("unroll") for (int m = 0; m < 4; ++m) _Pragma("unroll") for (int k = 0; k < 2; ++k) dst[m][k] = *(const LAS bf16x8*)(lds + PG8_SA(b, h) + aoff + m * 2048 + k * 1024); } while (0)
; #define PG8_LDB(dst, b, h) do { _Pragma("unroll") for (int n = 0; n < 2; ++n) _Pragma("unroll") for (int k = 0; k < 2; ++k) dst[n][k] = *(const LAS bf16x8*)(lds + PG8_SB(b, h) + boff + n * 2048 + k * 1024); } while (0)
; #define PG8_MMA(ai, bj, At, Bt) do { __builtin_amdgcn_s_setprio(1); _Pragma("unroll") for (int m = 0; m < 4; ++m) _Pragma("unroll") for (int n = 0; n < 2; ++n) _Pragma("unroll") for (int k = 0; k < 2; ++k) \
;         acc[ai][bj][m][n] = __builtin_amdgcn_mfma_f32_16x16x32_bf16(Bt[n][k], At[m][k], acc[ai][bj][m][n], 0, 0, 0); __builtin_amdgcn_s_setprio(0); } while (0)
; #define PG8_WAIT_V(n) asm volatile("s_waitcnt vmcnt(" #n ")" ::: "memory")
; #define PG8_WAIT_L(n) asm volatile("s_waitcnt lgkmcnt(" #n ")" ::: "memory")
; #define PG8_BAR __builtin_amdgcn_s_barrier()
; #define PG8_SCHED __builtin_amdgcn_sched_barrier(0)
; template <class Epi, class Sched, int KC, bool ALIGN_EPI = false, bool SP2 = false, bool ATILED = false>
; __device__ __forceinline__ void gemm_phase(LAS unsigned char* lds, const Gemm g, const Sched& S, const Epi& E, int wave_s) {
;     ...
;             PG8_LDB(B0, 0, 0); PG8_LDB(B1, 0, 1); PG8_SCHED; PG8_LDA(At, 0, 0); PG8_STAGE(PG8_SA(1, 1), a1 + hstepA, voffA);
;             PG8_WAIT_V(8); PG8_WAIT_L(0); PG8_BAR; PG8_MMA(0, 0, At, B0); PG8_MMA(0, 1, At, B1); PG8_BAR; PG8_SCHED;
;             PG8_LDA(At, 0, 1); PG8_STAGE(PG8_SB(0, 0), b2, voffB); PG8_STAGE(PG8_SB(0, 1), b2 + hstepB, voffB); PG8_STAGE(PG8_SA(0, 0), a2, voffA);
;             PG8_WAIT_V(8); PG8_WAIT_L(0); PG8_BAR; PG8_MMA(1, 0, At, B0); PG8_MMA(1, 1, At, B1); PG8_BAR; PG8_SCHED;
	s_waitcnt lgkmcnt(0)
	v_mfma_f32_16x16x32_bf16 v[126:129], v[152:155], v[198:201], v[126:129]
	v_mfma_f32_16x16x32_bf16 v[122:125], v[174:177], v[198:201], v[122:125]
	v_mfma_f32_16x16x32_bf16 v[114:117], v[152:155], v[206:209], v[114:117]
	v_mfma_f32_16x16x32_bf16 v[106:109], v[174:177], v[206:209], v[106:109]
	v_mfma_f32_16x16x32_bf16 v[98:101], v[152:155], v[214:217], v[98:101]
	v_mfma_f32_16x16x32_bf16 v[90:93], v[174:177], v[214:217], v[90:93]
	v_mfma_f32_16x16x32_bf16 v[82:85], v[152:155], v[222:225], v[82:85]
	v_mfma_f32_16x16x32_bf16 v[74:77], v[174:177], v[222:225], v[74:77]
	v_mfma_f32_16x16x32_bf16 v[126:129], v[160:163], v[202:205], v[126:129]
	v_mfma_f32_16x16x32_bf16 v[122:125], v[178:181], v[202:205], v[122:125]
	v_mfma_f32_16x16x32_bf16 v[114:117], v[160:163], v[210:213], v[114:117]
	v_mfma_f32_16x16x32_bf16 v[106:109], v[178:181], v[210:213], v[106:109]
	v_mfma_f32_16x16x32_bf16 v[98:101], v[160:163], v[218:221], v[98:101]
	v_mfma_f32_16x16x32_bf16 v[90:93], v[178:181], v[218:221], v[90:93]
	v_mfma_f32_16x16x32_bf16 v[82:85], v[160:163], v[226:229], v[82:85]
	v_mfma_f32_16x16x32_bf16 v[74:77], v[178:181], v[226:229], v[74:77]
	v_mfma_f32_16x16x32_bf16 v[118:121], v[182:185], v[198:201], v[118:121]
	v_mfma_f32_16x16x32_bf16 v[110:113], v[190:193], v[198:201], v[110:113]
	v_mfma_f32_16x16x32_bf16 v[102:105], v[182:185], v[206:209], v[102:105]
	v_mfma_f32_16x16x32_bf16 v[94:97], v[190:193], v[206:209], v[94:97]
	v_mfma_f32_16x16x32_bf16 v[86:89], v[182:185], v[214:217], v[86:89]
	v_mfma_f32_16x16x32_bf16 v[78:81], v[190:193], v[214:217], v[78:81]
	v_mfma_f32_16x16x32_bf16 v[70:73], v[182:185], v[222:225], v[70:73]
	v_mfma_f32_16x16x32_bf16 v[66:69], v[190:193], v[222:225], v[66:69]
	v_mfma_f32_16x16x32_bf16 v[118:121], v[186:189], v[202:205], v[118:121]
	v_mfma_f32_16x16x32_bf16 v[110:113], v[194:197], v[202:205], v[110:113]
	v_mfma_f32_16x16x32_bf16 v[102:105], v[186:189], v[210:213], v[102:105]
	v_mfma_f32_16x16x32_bf16 v[94:97], v[194:197], v[210:213], v[94:97]
	v_mfma_f32_16x16x32_bf16 v[86:89], v[186:189], v[218:221], v[86:89]
	v_mfma_f32_16x16x32_bf16 v[78:81], v[194:197], v[218:221], v[78:81]
	v_mfma_f32_16x16x32_bf16 v[70:73], v[186:189], v[226:229], v[70:73]
	v_mfma_f32_16x16x32_bf16 v[66:69], v[194:197], v[226:229], v[66:69]
	s_barrier
	s_add_u32 s100, s34, 0x80
	s_addc_u32 s101, s35, 0
	s_add_i32 s67, s70, s41
	s_mov_b32 m0, s67
	ds_read_b128 v[198:201], v173 offset:16384
	ds_read_b128 v[202:205], v173 offset:17408
	ds_read_b128 v[206:209], v173 offset:18432
	ds_read_b128 v[210:213], v173 offset:19456
	ds_read_b128 v[214:217], v173 offset:20480
	ds_read_b128 v[218:221], v173 offset:21504
	ds_read_b128 v[222:225], v173 offset:22528
	ds_read_b128 v[226:229], v173 offset:23552
	global_load_lds_dwordx4 v134, s[28:29]
	s_add_i32 m0, s67, 0x2000
	s_add_u32 s68, s28, 0x80000
	s_addc_u32 s69, s29, 0
	s_add_i32 s67, s71, s41
	global_load_lds_dwordx4 v130, s[28:29]
	s_mov_b32 m0, s67
	s_nop 0
	global_load_lds_dwordx4 v134, s[68:69]
	s_add_i32 m0, s67, 0x2000
	s_nop 0
	global_load_lds_dwordx4 v130, s[68:69]
	s_mov_b32 m0, s25
	s_nop 0
	global_load_lds_dwordx4 v136, s[34:35]
	s_mov_b32 m0, s52
	s_nop 0
	global_load_lds_dwordx4 v132, s[34:35]
	s_waitcnt vmcnt(24)
	s_waitcnt lgkmcnt(0)
	s_barrier
	s_waitcnt lgkmcnt(0)
	v_mfma_f32_16x16x32_bf16 v[62:65], v[152:155], v[198:201], v[62:65]
	v_mfma_f32_16x16x32_bf16 v[58:61], v[174:177], v[198:201], v[58:61]
	v_mfma_f32_16x16x32_bf16 v[50:53], v[152:155], v[206:209], v[50:53]
	v_mfma_f32_16x16x32_bf16 v[42:45], v[174:177], v[206:209], v[42:45]
	v_mfma_f32_16x16x32_bf16 v[34:37], v[152:155], v[214:217], v[34:37]
	v_mfma_f32_16x16x32_bf16 v[26:29], v[174:177], v[214:217], v[26:29]
	v_mfma_f32_16x16x32_bf16 v[18:21], v[152:155], v[222:225], v[18:21]
	v_mfma_f32_16x16x32_bf16 v[10:13], v[174:177], v[222:225], v[10:13]
	v_mfma_f32_16x16x32_bf16 v[62:65], v[160:163], v[202:205], v[62:65]
	v_mfma_f32_16x16x32_bf16 v[58:61], v[178:181], v[202:205], v[58:61]
	v_mfma_f32_16x16x32_bf16 v[50:53], v[160:163], v[210:213], v[50:53]
	v_mfma_f32_16x16x32_bf16 v[42:45], v[178:181], v[210:213], v[42:45]
	v_mfma_f32_16x16x32_bf16 v[34:37], v[160:163], v[218:221], v[34:37]
	v_mfma_f32_16x16x32_bf16 v[26:29], v[178:181], v[218:221], v[26:29]
	v_mfma_f32_16x16x32_bf16 v[18:21], v[160:163], v[226:229], v[18:21]
	v_mfma_f32_16x16x32_bf16 v[10:13], v[178:181], v[226:229], v[10:13]
	v_mfma_f32_16x16x32_bf16 v[54:57], v[182:185], v[198:201], v[54:57]
	v_mfma_f32_16x16x32_bf16 v[46:49], v[190:193], v[198:201], v[46:49]
	v_mfma_f32_16x16x32_bf16 v[38:41], v[182:185], v[206:209], v[38:41]
	v_mfma_f32_16x16x32_bf16 v[30:33], v[190:193], v[206:209], v[30:33]
	v_mfma_f32_16x16x32_bf16 v[22:25], v[182:185], v[214:217], v[22:25]
	v_mfma_f32_16x16x32_bf16 v[14:17], v[190:193], v[214:217], v[14:17]
	v_mfma_f32_16x16x32_bf16 v[6:9], v[182:185], v[222:225], v[6:9]
	v_mfma_f32_16x16x32_bf16 v[2:5], v[190:193], v[222:225], v[2:5]
	v_mfma_f32_16x16x32_bf16 v[54:57], v[186:189], v[202:205], v[54:57]
	v_mfma_f32_16x16x32_bf16 v[46:49], v[194:197], v[202:205], v[46:49]
	v_mfma_f32_16x16x32_bf16 v[38:41], v[186:189], v[210:213], v[38:41]
	v_mfma_f32_16x16x32_bf16 v[30:33], v[194:197], v[210:213], v[30:33]
	v_mfma_f32_16x16x32_bf16 v[22:25], v[186:189], v[218:221], v[22:25]
	v_mfma_f32_16x16x32_bf16 v[14:17], v[194:197], v[218:221], v[14:17]
	v_mfma_f32_16x16x32_bf16 v[6:9], v[186:189], v[226:229], v[6:9]
	v_mfma_f32_16x16x32_bf16 v[2:5], v[194:197], v[226:229], v[2:5]
	s_barrier
; #define PG8_STAGE(bufoff, gbase, voff) do { _Pragma("unroll") for (int _i = 0; _i < 2; ++_i) \
;         __builtin_amdgcn_global_load_lds((const unsigned*)((const char*)(gbase) + (voff)[_i]), (LAS unsigned*)(lds + (bufoff) + ldsw + _i * 8192), 16, 0, 0); } while (0)
; #define PG8_LDA(dst, b, h) do { _Pragma("unroll") for (int m = 0; m < 4; ++m) _Pragma("unroll") for (int k = 0; k < 2; ++k) dst[m][k] = *(const LAS bf16x8*)(lds + PG8_SA(b, h) + aoff + m * 2048 + k * 1024); } while (0)
; #define PG8_LDB(dst, b, h) do { _Pragma("unroll") for (int n = 0; n < 2; ++n) _Pragma("unroll") for (int k = 0; k < 2; ++k) dst[n][k] = *(const LAS bf16x8*)(lds + PG8_SB(b, h) + boff + n * 2048 + k * 1024); } while (0)
; #define PG8_MMA(ai, bj, At, Bt) do { __builtin_amdgcn_s_setprio(1); _Pragma("unroll") for (int m = 0; m < 4; ++m) _Pragma("unroll") for (int n = 0; n < 2; ++n) _Pragma("unroll") for (int k = 0; k < 2; ++k) \
;         acc[ai][bj][m][n] = __builtin_amdgcn_mfma_f32_16x16x32_bf16(Bt[n][k], At[m][k], acc[ai][bj][m][n], 0, 0, 0); __builtin_amdgcn_s_setprio(0); } while (0)
; #define PG8_WAIT_V(n) asm volatile("s_waitcnt vmcnt(" #n ")" ::: "memory")
; #define PG8_WAIT_L(n) asm volatile("s_waitcnt lgkmcnt(" #n ")" ::: "memory")
; #define PG8_BAR __builtin_amdgcn_s_barrier()
; #define PG8_SCHED __builtin_amdgcn_sched_barrier(0)
; template <class Epi, class Sched, int KC, bool ALIGN_EPI = false, bool SP2 = false, bool ATILED = false>
; __device__ __forceinline__ void gemm_phase(LAS unsigned char* lds, const Gemm g, const Sched& S, const Epi& E, int wave_s) {
;     ...
;             PG8_LDB(B0, 1, 0); PG8_LDB(B1, 1, 1); PG8_SCHED; PG8_LDA(At, 1, 0); PG8_STAGE(PG8_SA(0, 1), a2 + hstepA, voffA);
;             PG8_WAIT_V(8); PG8_WAIT_L(0); PG8_BAR; PG8_MMA(0, 0, At, B0); PG8_MMA(0, 1, At, B1); PG8_BAR; PG8_SCHED;
;             PG8_LDA(At, 1, 1); PG8_STAGE(PG8_SB(1, 0), b3, voffB); PG8_STAGE(PG8_SB(1, 1), b3 + hstepB, voffB); PG8_STAGE(PG8_SA(1, 0), a3, voffA);
;             PG8_WAIT_V(8); PG8_WAIT_L(0); PG8_BAR; PG8_MMA(1, 0, At, B0); PG8_MMA(1, 1, At, B1); PG8_BAR; PG8_SCHED;
	s_add_i32 s67, 0, 0x18000
	v_add_u32_e32 v139, s67, v165
	s_add_i32 s68, 0, 0x1c000
	ds_read_b128 v[152:155], v139
	ds_read_b128 v[160:163], v139 offset:1024
	ds_read_b128 v[174:177], v139 offset:2048
	ds_read_b128 v[178:181], v139 offset:3072
	v_add_u32_e32 v139, s68, v165
	ds_read_b128 v[182:185], v139
	ds_read_b128 v[186:189], v139 offset:1024
	ds_read_b128 v[190:193], v139 offset:2048
	ds_read_b128 v[194:197], v139 offset:3072
	s_add_u32 s34, s34, 0x10000
	s_addc_u32 s35, s35, 0
	s_mov_b32 m0, s53
	ds_read_b128 v[198:201], v173 offset:32768
	ds_read_b128 v[202:205], v173 offset:33792
	ds_read_b128 v[206:209], v173 offset:34816
	ds_read_b128 v[210:213], v173 offset:35840
	ds_read_b128 v[214:217], v173 offset:36864
	ds_read_b128 v[218:221], v173 offset:37888
	ds_read_b128 v[222:225], v173 offset:38912
	ds_read_b128 v[226:229], v173 offset:39936
	global_load_lds_dwordx4 v136, s[34:35]
	s_mov_b32 m0, s54
	s_nop 0
	global_load_lds_dwordx4 v132, s[34:35]
	s_waitcnt vmcnt(8)
	s_waitcnt lgkmcnt(0)
	s_barrier
	s_waitcnt lgkmcnt(0)
	v_mfma_f32_16x16x32_bf16 v[126:129], v[152:155], v[198:201], v[126:129]
	v_mfma_f32_16x16x32_bf16 v[122:125], v[174:177], v[198:201], v[122:125]
	v_mfma_f32_16x16x32_bf16 v[114:117], v[152:155], v[206:209], v[114:117]
	v_mfma_f32_16x16x32_bf16 v[106:109], v[174:177], v[206:209], v[106:109]
	v_mfma_f32_16x16x32_bf16 v[98:101], v[152:155], v[214:217], v[98:101]
	v_mfma_f32_16x16x32_bf16 v[90:93], v[174:177], v[214:217], v[90:93]
	v_mfma_f32_16x16x32_bf16 v[82:85], v[152:155], v[222:225], v[82:85]
	v_mfma_f32_16x16x32_bf16 v[74:77], v[174:177], v[222:225], v[74:77]
	v_mfma_f32_16x16x32_bf16 v[126:129], v[160:163], v[202:205], v[126:129]
	v_mfma_f32_16x16x32_bf16 v[122:125], v[178:181], v[202:205], v[122:125]
	v_mfma_f32_16x16x32_bf16 v[114:117], v[160:163], v[210:213], v[114:117]
	v_mfma_f32_16x16x32_bf16 v[106:109], v[178:181], v[210:213], v[106:109]
	v_mfma_f32_16x16x32_bf16 v[98:101], v[160:163], v[218:221], v[98:101]
	v_mfma_f32_16x16x32_bf16 v[90:93], v[178:181], v[218:221], v[90:93]
	v_mfma_f32_16x16x32_bf16 v[82:85], v[160:163], v[226:229], v[82:85]
	v_mfma_f32_16x16x32_bf16 v[74:77], v[178:181], v[226:229], v[74:77]
	v_mfma_f32_16x16x32_bf16 v[118:121], v[182:185], v[198:201], v[118:121]
	v_mfma_f32_16x16x32_bf16 v[110:113], v[190:193], v[198:201], v[110:113]
	v_mfma_f32_16x16x32_bf16 v[102:105], v[182:185], v[206:209], v[102:105]
	v_mfma_f32_16x16x32_bf16 v[94:97], v[190:193], v[206:209], v[94:97]
	v_mfma_f32_16x16x32_bf16 v[86:89], v[182:185], v[214:217], v[86:89]
	v_mfma_f32_16x16x32_bf16 v[78:81], v[190:193], v[214:217], v[78:81]
	v_mfma_f32_16x16x32_bf16 v[70:73], v[182:185], v[222:225], v[70:73]
	v_mfma_f32_16x16x32_bf16 v[66:69], v[190:193], v[222:225], v[66:69]
	v_mfma_f32_16x16x32_bf16 v[118:121], v[186:189], v[202:205], v[118:121]
	v_mfma_f32_16x16x32_bf16 v[110:113], v[194:197], v[202:205], v[110:113]
	v_mfma_f32_16x16x32_bf16 v[102:105], v[186:189], v[210:213], v[102:105]
	v_mfma_f32_16x16x32_bf16 v[94:97], v[194:197], v[210:213], v[94:97]
	v_mfma_f32_16x16x32_bf16 v[86:89], v[186:189], v[218:221], v[86:89]
	v_mfma_f32_16x16x32_bf16 v[78:81], v[194:197], v[218:221], v[78:81]
	v_mfma_f32_16x16x32_bf16 v[70:73], v[186:189], v[226:229], v[70:73]
	v_mfma_f32_16x16x32_bf16 v[66:69], v[194:197], v[226:229], v[66:69]
	s_barrier
	s_add_u32 s98, s28, 0x80
	s_addc_u32 s99, s29, 0
	s_add_i32 s34, s67, s41
	s_mov_b32 m0, s34
	ds_read_b128 v[198:201], v173 offset:49152
	ds_read_b128 v[202:205], v173 offset:50176
	ds_read_b128 v[206:209], v173 offset:51200
	ds_read_b128 v[210:213], v173 offset:52224
	ds_read_b128 v[214:217], v173 offset:53248
	ds_read_b128 v[218:221], v173 offset:54272
	ds_read_b128 v[222:225], v173 offset:55296
	ds_read_b128 v[226:229], v173 offset:56320
	global_load_lds_dwordx4 v134, s[98:99]
	s_add_i32 m0, s34, 0x2000
	s_add_u32 s28, s28, 0x80080
	s_addc_u32 s29, s29, 0
	s_add_i32 s34, s68, s41
	global_load_lds_dwordx4 v130, s[98:99]
	s_mov_b32 m0, s34
	s_nop 0
	global_load_lds_dwordx4 v134, s[28:29]
	s_add_i32 m0, s34, 0x2000
	s_nop 0
	global_load_lds_dwordx4 v130, s[28:29]
	s_mov_b32 m0, s55
	s_nop 0
	global_load_lds_dwordx4 v136, s[100:101]
	s_mov_b32 m0, s56
	s_nop 0
	global_load_lds_dwordx4 v132, s[100:101]
	s_waitcnt vmcnt(8)
	s_waitcnt lgkmcnt(0)
	s_barrier
	s_waitcnt lgkmcnt(0)
	v_mfma_f32_16x16x32_bf16 v[62:65], v[152:155], v[198:201], v[62:65]
	v_mfma_f32_16x16x32_bf16 v[58:61], v[174:177], v[198:201], v[58:61]
	v_mfma_f32_16x16x32_bf16 v[50:53], v[152:155], v[206:209], v[50:53]
	v_mfma_f32_16x16x32_bf16 v[42:45], v[174:177], v[206:209], v[42:45]
	v_mfma_f32_16x16x32_bf16 v[34:37], v[152:155], v[214:217], v[34:37]
	v_mfma_f32_16x16x32_bf16 v[26:29], v[174:177], v[214:217], v[26:29]
	v_mfma_f32_16x16x32_bf16 v[18:21], v[152:155], v[222:225], v[18:21]
	v_mfma_f32_16x16x32_bf16 v[10:13], v[174:177], v[222:225], v[10:13]
	v_mfma_f32_16x16x32_bf16 v[62:65], v[160:163], v[202:205], v[62:65]
	v_mfma_f32_16x16x32_bf16 v[58:61], v[178:181], v[202:205], v[58:61]
	v_mfma_f32_16x16x32_bf16 v[50:53], v[160:163], v[210:213], v[50:53]
	v_mfma_f32_16x16x32_bf16 v[42:45], v[178:181], v[210:213], v[42:45]
	v_mfma_f32_16x16x32_bf16 v[34:37], v[160:163], v[218:221], v[34:37]
	v_mfma_f32_16x16x32_bf16 v[26:29], v[178:181], v[218:221], v[26:29]
	v_mfma_f32_16x16x32_bf16 v[18:21], v[160:163], v[226:229], v[18:21]
	v_mfma_f32_16x16x32_bf16 v[10:13], v[178:181], v[226:229], v[10:13]
	v_mfma_f32_16x16x32_bf16 v[54:57], v[182:185], v[198:201], v[54:57]
	v_mfma_f32_16x16x32_bf16 v[46:49], v[190:193], v[198:201], v[46:49]
	v_mfma_f32_16x16x32_bf16 v[38:41], v[182:185], v[206:209], v[38:41]
	v_mfma_f32_16x16x32_bf16 v[30:33], v[190:193], v[206:209], v[30:33]
	v_mfma_f32_16x16x32_bf16 v[22:25], v[182:185], v[214:217], v[22:25]
	v_mfma_f32_16x16x32_bf16 v[14:17], v[190:193], v[214:217], v[14:17]
	v_mfma_f32_16x16x32_bf16 v[6:9], v[182:185], v[222:225], v[6:9]
	v_mfma_f32_16x16x32_bf16 v[2:5], v[190:193], v[222:225], v[2:5]
	v_mfma_f32_16x16x32_bf16 v[54:57], v[186:189], v[202:205], v[54:57]
	v_mfma_f32_16x16x32_bf16 v[46:49], v[194:197], v[202:205], v[46:49]
	v_mfma_f32_16x16x32_bf16 v[38:41], v[186:189], v[210:213], v[38:41]
	v_mfma_f32_16x16x32_bf16 v[30:33], v[194:197], v[210:213], v[30:33]
	v_mfma_f32_16x16x32_bf16 v[22:25], v[186:189], v[218:221], v[22:25]
	v_mfma_f32_16x16x32_bf16 v[14:17], v[194:197], v[218:221], v[14:17]
	v_mfma_f32_16x16x32_bf16 v[6:9], v[186:189], v[226:229], v[6:9]
	v_mfma_f32_16x16x32_bf16 v[2:5], v[194:197], v[226:229], v[2:5]
	s_barrier
	s_add_i32 s65, s65, 2
	s_add_i32 s66, s66, 0x400000
	s_cmp_gt_u32 s65, 29
	s_mov_b64 s[28:29], s[30:31]
	.p2align 6

; #define PG8_STAGE(bufoff, gbase, voff) do { _Pragma("unroll") for (int _i = 0; _i < 2; ++_i) \
;         __builtin_amdgcn_global_load_lds((const unsigned*)((const char*)(gbase) + (voff)[_i]), (LAS unsigned*)(lds + (bufoff) + ldsw + _i * 8192), 16, 0, 0); } while (0)
; #define PG8_LDA(dst, b, h) do { _Pragma("unroll") for (int m = 0; m < 4; ++m) _Pragma("unroll") for (int k = 0; k < 2; ++k) dst[m][k] = *(const LAS bf16x8*)(lds + PG8_SA(b, h) + aoff + m * 2048 + k * 1024); } while (0)
; #define PG8_LDB(dst, b, h) do { _Pragma("unroll") for (int n = 0; n < 2; ++n) _Pragma("unroll") for (int k = 0; k < 2; ++k) dst[n][k] = *(const LAS bf16x8*)(lds + PG8_SB(b, h) + boff + n * 2048 + k * 1024); } while (0)
; #define PG8_WAIT_V(n) asm volatile("s_waitcnt vmcnt(" #n ")" ::: "memory")
; #define PG8_WAIT_L(n) asm volatile("s_waitcnt lgkmcnt(" #n ")" ::: "memory")
; #define PG8_BAR __builtin_amdgcn_s_barrier()
; template <class Epi, class Sched, int KC, bool ALIGN_EPI = false, bool SP2 = false, bool ATILED = false>
; __device__ __forceinline__ void gemm_phase(LAS unsigned char* lds, const Gemm g, const Sched& S, const Epi& E, int wave_s) {
;     ...
;         const bool has_next = S.next(ui + 1, nxt);
;         const char* nA = has_next ? (const char*)g.A + (size_t)nxt.pm * tstepA : cA; const char* nB = has_next ? (const char*)g.Bt + (size_t)nxt.pn * tstep : cB;
;         for (int t = 0; t < nt; t += 2) {
;             const bool last = (t == nt - 2);
;             const char* a1 = cA + PG8_AOFF(t + 1);
;             const char* a2 = last ? nA : cA + PG8_AOFF(t + 2); const char* b2 = last ? nB : cB + (size_t)(t + 2) * kstep;
;             const char* a3 = a2 + kstep; const char* b3 = b2 + kstep;
;             if (last && has_next) S.a_ready(nxt);
;             if constexpr (SP2) {
;             PG8_LDB(B0, 0, 0); PG8_LDB(B1, 0, 1); PG8_SCHED; PG8_LDA(At, 0, 0); PG8_STAGE(PG8_SA(1, 1), a1 + hstepA, voffA);
;             PG8_WAIT_V(8); PG8_WAIT_L(0); PG8_BAR; PG8_MMA(0, 0, At, B0); PG8_MMA(0, 1, At, B1); PG8_BAR; PG8_SCHED;
;     ...
; #pragma unroll
;         for (int a = 0; a < 2; ++a)
; #pragma unroll
;             for (int b = 0; b < 2; ++b)
; #pragma unroll
;                 for (int m = 0; m < 4; ++m)
; #pragma unroll
;                     for (int n = 0; n < 2; ++n) acc[a][b][m][n] = (f32x4){0.f, 0.f, 0.f, 0.f};
;         cur = nxt; cA = nA; cB = nB; ++ui;
.LBB0_1020:
	v_mov_b64_e32 v[2:3], 0x200
	s_ashr_i32 s9, s8, 31
	v_cmp_lt_i64_e32 vcc, s[10:11], v[2:3]
	s_lshl_b64 s[10:11], s[8:9], 20
	s_add_u32 s10, s27, s10
	s_addc_u32 s11, s28, s11
	s_and_b64 s[12:13], vcc, exec
	s_cselect_b32 s9, s11, s21
	s_cselect_b32 s15, s10, s20
	s_ashr_i32 s3, s2, 31
	s_lshl_b64 s[12:13], s[2:3], 20
	s_add_u32 s12, s29, s12
	s_addc_u32 s13, s30, s13
	s_and_b64 s[22:23], vcc, exec
	s_cselect_b32 s3, s13, s19
	s_cselect_b32 s17, s12, s18
	s_add_u32 s46, s18, 0x100
	s_addc_u32 s47, s19, 0
	s_add_u32 s18, s20, 0x80080
	v_mov_b32_e32 v2, 0
	s_addc_u32 s19, s21, 0
	s_mov_b32 s48, -2
	v_mov_b32_e32 v3, v2
	v_mov_b32_e32 v4, v2
	v_mov_b32_e32 v5, v2
	v_mov_b32_e32 v6, v2
	v_mov_b32_e32 v7, v2
	v_mov_b32_e32 v8, v2
	v_mov_b32_e32 v9, v2
	v_mov_b32_e32 v18, v2
	v_mov_b32_e32 v19, v2
	v_mov_b32_e32 v20, v2
	v_mov_b32_e32 v21, v2
	v_mov_b32_e32 v22, v2
	v_mov_b32_e32 v23, v2
	v_mov_b32_e32 v24, v2
	v_mov_b32_e32 v25, v2
	v_mov_b32_e32 v34, v2
	v_mov_b32_e32 v35, v2
	v_mov_b32_e32 v36, v2
	v_mov_b32_e32 v37, v2
	v_mov_b32_e32 v38, v2
	v_mov_b32_e32 v39, v2
	v_mov_b32_e32 v40, v2
	v_mov_b32_e32 v41, v2
	v_mov_b32_e32 v50, v2
	v_mov_b32_e32 v51, v2
	v_mov_b32_e32 v52, v2
	v_mov_b32_e32 v53, v2
	v_mov_b32_e32 v54, v2
	v_mov_b32_e32 v55, v2
	v_mov_b32_e32 v56, v2
	v_mov_b32_e32 v57, v2
	v_mov_b32_e32 v10, v2
	v_mov_b32_e32 v11, v2
	v_mov_b32_e32 v12, v2
	v_mov_b32_e32 v13, v2
	v_mov_b32_e32 v14, v2
	v_mov_b32_e32 v15, v2
	v_mov_b32_e32 v16, v2
	v_mov_b32_e32 v17, v2
	v_mov_b32_e32 v26, v2
	v_mov_b32_e32 v27, v2
	v_mov_b32_e32 v28, v2
	v_mov_b32_e32 v29, v2
	v_mov_b32_e32 v30, v2
	v_mov_b32_e32 v31, v2
	v_mov_b32_e32 v32, v2
	v_mov_b32_e32 v33, v2
	v_mov_b32_e32 v42, v2
	v_mov_b32_e32 v43, v2
	v_mov_b32_e32 v44, v2
	v_mov_b32_e32 v45, v2
	v_mov_b32_e32 v46, v2
	v_mov_b32_e32 v47, v2
	v_mov_b32_e32 v48, v2
	v_mov_b32_e32 v49, v2
	v_mov_b32_e32 v58, v2
	v_mov_b32_e32 v59, v2
	v_mov_b32_e32 v60, v2
	v_mov_b32_e32 v61, v2
	v_mov_b32_e32 v62, v2
	v_mov_b32_e32 v63, v2
	v_mov_b32_e32 v64, v2
	v_mov_b32_e32 v65, v2
	v_mov_b32_e32 v66, v2
	v_mov_b32_e32 v67, v2
	v_mov_b32_e32 v68, v2
	v_mov_b32_e32 v69, v2
	v_mov_b32_e32 v70, v2
	v_mov_b32_e32 v71, v2
	v_mov_b32_e32 v72, v2
	v_mov_b32_e32 v73, v2
	s_waitcnt vmcnt(0)
	v_mov_b32_e32 v82, v2
	v_mov_b32_e32 v83, v2
	v_mov_b32_e32 v84, v2
	v_mov_b32_e32 v85, v2
	v_mov_b32_e32 v86, v2
	v_mov_b32_e32 v87, v2
	v_mov_b32_e32 v88, v2
	v_mov_b32_e32 v89, v2
	v_mov_b32_e32 v98, v2
	v_mov_b32_e32 v99, v2
	v_mov_b32_e32 v100, v2
	v_mov_b32_e32 v101, v2
	v_mov_b32_e32 v102, v2
	v_mov_b32_e32 v103, v2
	v_mov_b32_e32 v104, v2
	v_mov_b32_e32 v105, v2
	v_mov_b32_e32 v114, v2
	v_mov_b32_e32 v115, v2
	v_mov_b32_e32 v116, v2
	v_mov_b32_e32 v117, v2
	v_mov_b32_e32 v118, v2
	v_mov_b32_e32 v119, v2
	v_mov_b32_e32 v120, v2
	v_mov_b32_e32 v121, v2
	v_mov_b32_e32 v74, v2
	v_mov_b32_e32 v75, v2
	v_mov_b32_e32 v76, v2
	v_mov_b32_e32 v77, v2
	v_mov_b32_e32 v78, v2
	v_mov_b32_e32 v79, v2
	v_mov_b32_e32 v80, v2
	v_mov_b32_e32 v81, v2
	v_mov_b32_e32 v90, v2
	v_mov_b32_e32 v91, v2
	v_mov_b32_e32 v92, v2
	v_mov_b32_e32 v93, v2
	v_mov_b32_e32 v94, v2
	v_mov_b32_e32 v95, v2
	v_mov_b32_e32 v96, v2
	v_mov_b32_e32 v97, v2
	v_mov_b32_e32 v106, v2
	v_mov_b32_e32 v107, v2
	v_mov_b32_e32 v108, v2
	v_mov_b32_e32 v109, v2
	v_mov_b32_e32 v110, v2
	v_mov_b32_e32 v111, v2
	v_mov_b32_e32 v112, v2
	v_mov_b32_e32 v113, v2
	v_mov_b32_e32 v122, v2
	v_mov_b32_e32 v123, v2
	v_mov_b32_e32 v124, v2
	v_mov_b32_e32 v125, v2
	v_mov_b32_e32 v126, v2
	v_mov_b32_e32 v127, v2
	v_mov_b32_e32 v128, v2
	v_mov_b32_e32 v129, v2
	s_add_u32 s20, s18, 0xfff80080
	s_addc_u32 s21, s19, -1
	s_add_i32 s49, 0, 0x10000
	s_cmp_eq_u32 s48, 28
	s_cselect_b32 s23, s9, s21
	s_cselect_b32 s22, s15, s20
	s_cselect_b32 s21, s3, s47
	s_cselect_b32 s20, s17, s46
	s_add_i32 s52, 0, 0x14000
	v_add_u32_e32 v142, s49, v229
	v_add_u32_e32 v158, s52, v229
	ds_read_b128 v[130:133], v142
	ds_read_b128 v[134:137], v142 offset:1024
	ds_read_b128 v[138:141], v142 offset:2048
	ds_read_b128 v[142:145], v142 offset:3072
	ds_read_b128 v[146:149], v158
	ds_read_b128 v[150:153], v158 offset:1024
	ds_read_b128 v[154:157], v158 offset:2048
	ds_read_b128 v[158:161], v158 offset:3072
	s_add_i32 m0, s34, 0xc000
	ds_read_b128 v[162:165], v230
	ds_read_b128 v[166:169], v230 offset:1024
	ds_read_b128 v[170:173], v230 offset:2048
	ds_read_b128 v[174:177], v230 offset:3072
	ds_read_b128 v[178:181], v230 offset:4096
	ds_read_b128 v[182:185], v230 offset:5120
	ds_read_b128 v[186:189], v230 offset:6144
	ds_read_b128 v[190:193], v230 offset:7168
	global_load_lds_dwordx4 v208, s[18:19]
	s_add_i32 m0, s34, 0xe000
	s_nop 0
	global_load_lds_dwordx4 v206, s[18:19]
	s_waitcnt vmcnt(32)
	s_waitcnt lgkmcnt(0)
	s_barrier
; #define PG8_STAGE(bufoff, gbase, voff) do { _Pragma("unroll") for (int _i = 0; _i < 2; ++_i) \
;         __builtin_amdgcn_global_load_lds((const unsigned*)((const char*)(gbase) + (voff)[_i]), (LAS unsigned*)(lds + (bufoff) + ldsw + _i * 8192), 16, 0, 0); } while (0)
; #define PG8_LDA(dst, b, h) do { _Pragma("unroll") for (int m = 0; m < 4; ++m) _Pragma("unroll") for (int k = 0; k < 2; ++k) dst[m][k] = *(const LAS bf16x8*)(lds + PG8_SA(b, h) + aoff + m * 2048 + k * 1024); } while (0)
; #define PG8_LDB(dst, b, h) do { _Pragma("unroll") for (int n = 0; n < 2; ++n) _Pragma("unroll") for (int k = 0; k < 2; ++k) dst[n][k] = *(const LAS bf16x8*)(lds + PG8_SB(b, h) + boff + n * 2048 + k * 1024); } while (0)
; #define PG8_MMA(ai, bj, At, Bt) do { __builtin_amdgcn_s_setprio(1); _Pragma("unroll") for (int m = 0; m < 4; ++m) _Pragma("unroll") for (int n = 0; n < 2; ++n) _Pragma("unroll") for (int k = 0; k < 2; ++k) \
;         acc[ai][bj][m][n] = __builtin_amdgcn_mfma_f32_16x16x32_bf16(Bt[n][k], At[m][k], acc[ai][bj][m][n], 0, 0, 0); __builtin_amdgcn_s_setprio(0); } while (0)
; #define PG8_WAIT_V(n) asm volatile("s_waitcnt vmcnt(" #n ")" ::: "memory")
; #define PG8_WAIT_L(n) asm volatile("s_waitcnt lgkmcnt(" #n ")" ::: "memory")
; #define PG8_BAR __builtin_amdgcn_s_barrier()
; #define PG8_SCHED __builtin_amdgcn_sched_barrier(0)
; template <class Epi, class Sched, int KC, bool ALIGN_EPI = false, bool SP2 = false, bool ATILED = false>
; __device__ __forceinline__ void gemm_phase(LAS unsigned char* lds, const Gemm g, const Sched& S, const Epi& E, int wave_s) {
;     ...
;             PG8_LDB(B0, 0, 0); PG8_LDB(B1, 0, 1); PG8_SCHED; PG8_LDA(At, 0, 0); PG8_STAGE(PG8_SA(1, 1), a1 + hstepA, voffA);
;             PG8_WAIT_V(8); PG8_WAIT_L(0); PG8_BAR; PG8_MMA(0, 0, At, B0); PG8_MMA(0, 1, At, B1); PG8_BAR; PG8_SCHED;
;             PG8_LDA(At, 0, 1); PG8_STAGE(PG8_SB(0, 0), b2, voffB); PG8_STAGE(PG8_SB(0, 1), b2 + hstepB, voffB); PG8_STAGE(PG8_SA(0, 0), a2, voffA);
;             PG8_WAIT_V(8); PG8_WAIT_L(0); PG8_BAR; PG8_MMA(1, 0, At, B0); PG8_MMA(1, 1, At, B1); PG8_BAR; PG8_SCHED;
	s_waitcnt lgkmcnt(0)
	v_mfma_f32_16x16x32_bf16 v[126:129], v[130:133], v[162:165], v[126:129]
	v_mfma_f32_16x16x32_bf16 v[122:125], v[138:141], v[162:165], v[122:125]
	v_mfma_f32_16x16x32_bf16 v[110:113], v[130:133], v[170:173], v[110:113]
	v_mfma_f32_16x16x32_bf16 v[106:109], v[138:141], v[170:173], v[106:109]
	v_mfma_f32_16x16x32_bf16 v[94:97], v[130:133], v[178:181], v[94:97]
	v_mfma_f32_16x16x32_bf16 v[90:93], v[138:141], v[178:181], v[90:93]
	v_mfma_f32_16x16x32_bf16 v[78:81], v[130:133], v[186:189], v[78:81]
	v_mfma_f32_16x16x32_bf16 v[74:77], v[138:141], v[186:189], v[74:77]
	v_mfma_f32_16x16x32_bf16 v[126:129], v[134:137], v[166:169], v[126:129]
	v_mfma_f32_16x16x32_bf16 v[122:125], v[142:145], v[166:169], v[122:125]
	v_mfma_f32_16x16x32_bf16 v[110:113], v[134:137], v[174:177], v[110:113]
	v_mfma_f32_16x16x32_bf16 v[106:109], v[142:145], v[174:177], v[106:109]
	v_mfma_f32_16x16x32_bf16 v[94:97], v[134:137], v[182:185], v[94:97]
	v_mfma_f32_16x16x32_bf16 v[90:93], v[142:145], v[182:185], v[90:93]
	v_mfma_f32_16x16x32_bf16 v[78:81], v[134:137], v[190:193], v[78:81]
	v_mfma_f32_16x16x32_bf16 v[74:77], v[142:145], v[190:193], v[74:77]
	v_mfma_f32_16x16x32_bf16 v[118:121], v[146:149], v[162:165], v[118:121]
	v_mfma_f32_16x16x32_bf16 v[114:117], v[154:157], v[162:165], v[114:117]
	v_mfma_f32_16x16x32_bf16 v[102:105], v[146:149], v[170:173], v[102:105]
	v_mfma_f32_16x16x32_bf16 v[98:101], v[154:157], v[170:173], v[98:101]
	v_mfma_f32_16x16x32_bf16 v[86:89], v[146:149], v[178:181], v[86:89]
	v_mfma_f32_16x16x32_bf16 v[82:85], v[154:157], v[178:181], v[82:85]
	v_mfma_f32_16x16x32_bf16 v[70:73], v[146:149], v[186:189], v[70:73]
	v_mfma_f32_16x16x32_bf16 v[66:69], v[154:157], v[186:189], v[66:69]
	v_mfma_f32_16x16x32_bf16 v[118:121], v[150:153], v[166:169], v[118:121]
	v_mfma_f32_16x16x32_bf16 v[114:117], v[158:161], v[166:169], v[114:117]
	v_mfma_f32_16x16x32_bf16 v[102:105], v[150:153], v[174:177], v[102:105]
	v_mfma_f32_16x16x32_bf16 v[98:101], v[158:161], v[174:177], v[98:101]
	v_mfma_f32_16x16x32_bf16 v[86:89], v[150:153], v[182:185], v[86:89]
	v_mfma_f32_16x16x32_bf16 v[82:85], v[158:161], v[182:185], v[82:85]
	v_mfma_f32_16x16x32_bf16 v[70:73], v[150:153], v[190:193], v[70:73]
	v_mfma_f32_16x16x32_bf16 v[66:69], v[158:161], v[190:193], v[66:69]
	s_barrier
	s_add_u32 s100, s22, 0x80
	s_addc_u32 s101, s23, 0
	s_add_i32 s49, s49, s31
	s_mov_b32 m0, s49
	ds_read_b128 v[162:165], v230 offset:16384
	ds_read_b128 v[166:169], v230 offset:17408
	ds_read_b128 v[170:173], v230 offset:18432
	ds_read_b128 v[174:177], v230 offset:19456
	ds_read_b128 v[178:181], v230 offset:20480
	ds_read_b128 v[182:185], v230 offset:21504
	ds_read_b128 v[186:189], v230 offset:22528
	ds_read_b128 v[190:193], v230 offset:23552
	global_load_lds_dwordx4 v0, s[20:21]
	s_add_i32 m0, s49, 0x2000
	s_add_u32 s50, s20, 0x20000
	s_addc_u32 s51, s21, 0
	s_add_i32 s49, s52, s31
	global_load_lds_dwordx4 v202, s[20:21]
	s_mov_b32 m0, s49
	s_nop 0
	global_load_lds_dwordx4 v0, s[50:51]
	s_add_i32 m0, s49, 0x2000
	s_nop 0
	global_load_lds_dwordx4 v202, s[50:51]
	s_mov_b32 m0, s34
	s_nop 0
	global_load_lds_dwordx4 v198, s[22:23]
	s_mov_b32 m0, s35
	s_nop 0
	global_load_lds_dwordx4 v200, s[22:23]
	s_waitcnt vmcnt(32)
	s_waitcnt lgkmcnt(0)
	s_barrier
	s_waitcnt lgkmcnt(0)
	v_mfma_f32_16x16x32_bf16 v[62:65], v[130:133], v[162:165], v[62:65]
	v_mfma_f32_16x16x32_bf16 v[58:61], v[138:141], v[162:165], v[58:61]
	v_mfma_f32_16x16x32_bf16 v[46:49], v[130:133], v[170:173], v[46:49]
	v_mfma_f32_16x16x32_bf16 v[42:45], v[138:141], v[170:173], v[42:45]
	v_mfma_f32_16x16x32_bf16 v[30:33], v[130:133], v[178:181], v[30:33]
	v_mfma_f32_16x16x32_bf16 v[26:29], v[138:141], v[178:181], v[26:29]
	v_mfma_f32_16x16x32_bf16 v[14:17], v[130:133], v[186:189], v[14:17]
	v_mfma_f32_16x16x32_bf16 v[10:13], v[138:141], v[186:189], v[10:13]
	v_mfma_f32_16x16x32_bf16 v[62:65], v[134:137], v[166:169], v[62:65]
	v_mfma_f32_16x16x32_bf16 v[58:61], v[142:145], v[166:169], v[58:61]
	v_mfma_f32_16x16x32_bf16 v[46:49], v[134:137], v[174:177], v[46:49]
	v_mfma_f32_16x16x32_bf16 v[42:45], v[142:145], v[174:177], v[42:45]
	v_mfma_f32_16x16x32_bf16 v[30:33], v[134:137], v[182:185], v[30:33]
	v_mfma_f32_16x16x32_bf16 v[26:29], v[142:145], v[182:185], v[26:29]
	v_mfma_f32_16x16x32_bf16 v[14:17], v[134:137], v[190:193], v[14:17]
	v_mfma_f32_16x16x32_bf16 v[10:13], v[142:145], v[190:193], v[10:13]
	v_mfma_f32_16x16x32_bf16 v[54:57], v[146:149], v[162:165], v[54:57]
	v_mfma_f32_16x16x32_bf16 v[50:53], v[154:157], v[162:165], v[50:53]
	v_mfma_f32_16x16x32_bf16 v[38:41], v[146:149], v[170:173], v[38:41]
	v_mfma_f32_16x16x32_bf16 v[34:37], v[154:157], v[170:173], v[34:37]
	v_mfma_f32_16x16x32_bf16 v[22:25], v[146:149], v[178:181], v[22:25]
	v_mfma_f32_16x16x32_bf16 v[18:21], v[154:157], v[178:181], v[18:21]
	v_mfma_f32_16x16x32_bf16 v[6:9], v[146:149], v[186:189], v[6:9]
	v_mfma_f32_16x16x32_bf16 v[2:5], v[154:157], v[186:189], v[2:5]
	v_mfma_f32_16x16x32_bf16 v[54:57], v[150:153], v[166:169], v[54:57]
	v_mfma_f32_16x16x32_bf16 v[50:53], v[158:161], v[166:169], v[50:53]
	v_mfma_f32_16x16x32_bf16 v[38:41], v[150:153], v[174:177], v[38:41]
	v_mfma_f32_16x16x32_bf16 v[34:37], v[158:161], v[174:177], v[34:37]
	v_mfma_f32_16x16x32_bf16 v[22:25], v[150:153], v[182:185], v[22:25]
	v_mfma_f32_16x16x32_bf16 v[18:21], v[158:161], v[182:185], v[18:21]
	v_mfma_f32_16x16x32_bf16 v[6:9], v[150:153], v[190:193], v[6:9]
	v_mfma_f32_16x16x32_bf16 v[2:5], v[158:161], v[190:193], v[2:5]
	s_barrier
; #define PG8_STAGE(bufoff, gbase, voff) do { _Pragma("unroll") for (int _i = 0; _i < 2; ++_i) \
;         __builtin_amdgcn_global_load_lds((const unsigned*)((const char*)(gbase) + (voff)[_i]), (LAS unsigned*)(lds + (bufoff) + ldsw + _i * 8192), 16, 0, 0); } while (0)
; #define PG8_LDA(dst, b, h) do { _Pragma("unroll") for (int m = 0; m < 4; ++m) _Pragma("unroll") for (int k = 0; k < 2; ++k) dst[m][k] = *(const LAS bf16x8*)(lds + PG8_SA(b, h) + aoff + m * 2048 + k * 1024); } while (0)
; #define PG8_LDB(dst, b, h) do { _Pragma("unroll") for (int n = 0; n < 2; ++n) _Pragma("unroll") for (int k = 0; k < 2; ++k) dst[n][k] = *(const LAS bf16x8*)(lds + PG8_SB(b, h) + boff + n * 2048 + k * 1024); } while (0)
; #define PG8_MMA(ai, bj, At, Bt) do { __builtin_amdgcn_s_setprio(1); _Pragma("unroll") for (int m = 0; m < 4; ++m) _Pragma("unroll") for (int n = 0; n < 2; ++n) _Pragma("unroll") for (int k = 0; k < 2; ++k) \
;         acc[ai][bj][m][n] = __builtin_amdgcn_mfma_f32_16x16x32_bf16(Bt[n][k], At[m][k], acc[ai][bj][m][n], 0, 0, 0); __builtin_amdgcn_s_setprio(0); } while (0)
; #define PG8_WAIT_V(n) asm volatile("s_waitcnt vmcnt(" #n ")" ::: "memory")
; #define PG8_WAIT_L(n) asm volatile("s_waitcnt lgkmcnt(" #n ")" ::: "memory")
; #define PG8_BAR __builtin_amdgcn_s_barrier()
; #define PG8_SCHED __builtin_amdgcn_sched_barrier(0)
; template <class Epi, class Sched, int KC, bool ALIGN_EPI = false, bool SP2 = false, bool ATILED = false>
; __device__ __forceinline__ void gemm_phase(LAS unsigned char* lds, const Gemm g, const Sched& S, const Epi& E, int wave_s) {
;     ...
;             PG8_LDB(B0, 1, 0); PG8_LDB(B1, 1, 1); PG8_SCHED; PG8_LDA(At, 1, 0); PG8_STAGE(PG8_SA(0, 1), a2 + hstepA, voffA);
;             PG8_WAIT_V(8); PG8_WAIT_L(0); PG8_BAR; PG8_MMA(0, 0, At, B0); PG8_MMA(0, 1, At, B1); PG8_BAR; PG8_SCHED;
;             PG8_LDA(At, 1, 1); PG8_STAGE(PG8_SB(1, 0), b3, voffB); PG8_STAGE(PG8_SB(1, 1), b3 + hstepB, voffB); PG8_STAGE(PG8_SA(1, 0), a3, voffA);
;             PG8_WAIT_V(8); PG8_WAIT_L(0); PG8_BAR; PG8_MMA(1, 0, At, B0); PG8_MMA(1, 1, At, B1); PG8_BAR; PG8_SCHED;
	s_add_i32 s49, 0, 0x18000
	s_add_i32 s50, 0, 0x1c000
	v_add_u32_e32 v142, s49, v229
	v_add_u32_e32 v158, s50, v229
	ds_read_b128 v[130:133], v142
	ds_read_b128 v[134:137], v142 offset:1024
	ds_read_b128 v[138:141], v142 offset:2048
	ds_read_b128 v[142:145], v142 offset:3072
	ds_read_b128 v[146:149], v158
	ds_read_b128 v[150:153], v158 offset:1024
	ds_read_b128 v[154:157], v158 offset:2048
	ds_read_b128 v[158:161], v158 offset:3072
	s_add_u32 s22, s22, 0x80000
	s_addc_u32 s23, s23, 0
	s_mov_b32 m0, s36
	ds_read_b128 v[162:165], v230 offset:32768
	ds_read_b128 v[166:169], v230 offset:33792
	ds_read_b128 v[170:173], v230 offset:34816
	ds_read_b128 v[174:177], v230 offset:35840
	ds_read_b128 v[178:181], v230 offset:36864
	ds_read_b128 v[182:185], v230 offset:37888
	ds_read_b128 v[186:189], v230 offset:38912
	ds_read_b128 v[190:193], v230 offset:39936
	global_load_lds_dwordx4 v198, s[22:23]
	s_mov_b32 m0, s37
	s_nop 0
	global_load_lds_dwordx4 v200, s[22:23]
	s_waitcnt vmcnt(8)
	s_waitcnt lgkmcnt(0)
	s_barrier
	s_waitcnt lgkmcnt(0)
	v_mfma_f32_16x16x32_bf16 v[126:129], v[130:133], v[162:165], v[126:129]
	v_mfma_f32_16x16x32_bf16 v[122:125], v[138:141], v[162:165], v[122:125]
	v_mfma_f32_16x16x32_bf16 v[110:113], v[130:133], v[170:173], v[110:113]
	v_mfma_f32_16x16x32_bf16 v[106:109], v[138:141], v[170:173], v[106:109]
	v_mfma_f32_16x16x32_bf16 v[94:97], v[130:133], v[178:181], v[94:97]
	v_mfma_f32_16x16x32_bf16 v[90:93], v[138:141], v[178:181], v[90:93]
	v_mfma_f32_16x16x32_bf16 v[78:81], v[130:133], v[186:189], v[78:81]
	v_mfma_f32_16x16x32_bf16 v[74:77], v[138:141], v[186:189], v[74:77]
	v_mfma_f32_16x16x32_bf16 v[126:129], v[134:137], v[166:169], v[126:129]
	v_mfma_f32_16x16x32_bf16 v[122:125], v[142:145], v[166:169], v[122:125]
	v_mfma_f32_16x16x32_bf16 v[110:113], v[134:137], v[174:177], v[110:113]
	v_mfma_f32_16x16x32_bf16 v[106:109], v[142:145], v[174:177], v[106:109]
	v_mfma_f32_16x16x32_bf16 v[94:97], v[134:137], v[182:185], v[94:97]
	v_mfma_f32_16x16x32_bf16 v[90:93], v[142:145], v[182:185], v[90:93]
	v_mfma_f32_16x16x32_bf16 v[78:81], v[134:137], v[190:193], v[78:81]
	v_mfma_f32_16x16x32_bf16 v[74:77], v[142:145], v[190:193], v[74:77]
	v_mfma_f32_16x16x32_bf16 v[118:121], v[146:149], v[162:165], v[118:121]
	v_mfma_f32_16x16x32_bf16 v[114:117], v[154:157], v[162:165], v[114:117]
	v_mfma_f32_16x16x32_bf16 v[102:105], v[146:149], v[170:173], v[102:105]
	v_mfma_f32_16x16x32_bf16 v[98:101], v[154:157], v[170:173], v[98:101]
	v_mfma_f32_16x16x32_bf16 v[86:89], v[146:149], v[178:181], v[86:89]
	v_mfma_f32_16x16x32_bf16 v[82:85], v[154:157], v[178:181], v[82:85]
	v_mfma_f32_16x16x32_bf16 v[70:73], v[146:149], v[186:189], v[70:73]
	v_mfma_f32_16x16x32_bf16 v[66:69], v[154:157], v[186:189], v[66:69]
	v_mfma_f32_16x16x32_bf16 v[118:121], v[150:153], v[166:169], v[118:121]
	v_mfma_f32_16x16x32_bf16 v[114:117], v[158:161], v[166:169], v[114:117]
	v_mfma_f32_16x16x32_bf16 v[102:105], v[150:153], v[174:177], v[102:105]
	v_mfma_f32_16x16x32_bf16 v[98:101], v[158:161], v[174:177], v[98:101]
	v_mfma_f32_16x16x32_bf16 v[86:89], v[150:153], v[182:185], v[86:89]
	v_mfma_f32_16x16x32_bf16 v[82:85], v[158:161], v[182:185], v[82:85]
	v_mfma_f32_16x16x32_bf16 v[70:73], v[150:153], v[190:193], v[70:73]
	v_mfma_f32_16x16x32_bf16 v[66:69], v[158:161], v[190:193], v[66:69]
	s_barrier
	s_add_u32 s98, s20, 0x80
	s_addc_u32 s99, s21, 0
	s_add_i32 s22, s49, s31
	s_mov_b32 m0, s22
	ds_read_b128 v[162:165], v230 offset:49152
	ds_read_b128 v[166:169], v230 offset:50176
	ds_read_b128 v[170:173], v230 offset:51200
	ds_read_b128 v[174:177], v230 offset:52224
	ds_read_b128 v[178:181], v230 offset:53248
	ds_read_b128 v[182:185], v230 offset:54272
	ds_read_b128 v[186:189], v230 offset:55296
	ds_read_b128 v[190:193], v230 offset:56320
	global_load_lds_dwordx4 v0, s[98:99]
	s_add_i32 m0, s22, 0x2000
	s_add_u32 s20, s20, 0x20080
	s_addc_u32 s21, s21, 0
	s_add_i32 s22, s50, s31
	global_load_lds_dwordx4 v202, s[98:99]
	s_mov_b32 m0, s22
	s_nop 0
	global_load_lds_dwordx4 v0, s[20:21]
	s_add_i32 m0, s22, 0x2000
	s_nop 0
	global_load_lds_dwordx4 v202, s[20:21]
	s_mov_b32 m0, s41
	s_nop 0
	global_load_lds_dwordx4 v198, s[100:101]
	s_mov_b32 m0, s42
	s_nop 0
	global_load_lds_dwordx4 v200, s[100:101]
	s_waitcnt vmcnt(8)
	s_waitcnt lgkmcnt(0)
	s_barrier
	s_waitcnt lgkmcnt(0)
	v_mfma_f32_16x16x32_bf16 v[62:65], v[130:133], v[162:165], v[62:65]
	v_mfma_f32_16x16x32_bf16 v[58:61], v[138:141], v[162:165], v[58:61]
	v_mfma_f32_16x16x32_bf16 v[46:49], v[130:133], v[170:173], v[46:49]
	v_mfma_f32_16x16x32_bf16 v[42:45], v[138:141], v[170:173], v[42:45]
	v_mfma_f32_16x16x32_bf16 v[30:33], v[130:133], v[178:181], v[30:33]
	v_mfma_f32_16x16x32_bf16 v[26:29], v[138:141], v[178:181], v[26:29]
	v_mfma_f32_16x16x32_bf16 v[14:17], v[130:133], v[186:189], v[14:17]
	v_mfma_f32_16x16x32_bf16 v[10:13], v[138:141], v[186:189], v[10:13]
	v_mfma_f32_16x16x32_bf16 v[62:65], v[134:137], v[166:169], v[62:65]
	v_mfma_f32_16x16x32_bf16 v[58:61], v[142:145], v[166:169], v[58:61]
	v_mfma_f32_16x16x32_bf16 v[46:49], v[134:137], v[174:177], v[46:49]
	v_mfma_f32_16x16x32_bf16 v[42:45], v[142:145], v[174:177], v[42:45]
	v_mfma_f32_16x16x32_bf16 v[30:33], v[134:137], v[182:185], v[30:33]
	v_mfma_f32_16x16x32_bf16 v[26:29], v[142:145], v[182:185], v[26:29]
	v_mfma_f32_16x16x32_bf16 v[14:17], v[134:137], v[190:193], v[14:17]
	v_mfma_f32_16x16x32_bf16 v[10:13], v[142:145], v[190:193], v[10:13]
	v_mfma_f32_16x16x32_bf16 v[54:57], v[146:149], v[162:165], v[54:57]
	v_mfma_f32_16x16x32_bf16 v[50:53], v[154:157], v[162:165], v[50:53]
	v_mfma_f32_16x16x32_bf16 v[38:41], v[146:149], v[170:173], v[38:41]
	v_mfma_f32_16x16x32_bf16 v[34:37], v[154:157], v[170:173], v[34:37]
	v_mfma_f32_16x16x32_bf16 v[22:25], v[146:149], v[178:181], v[22:25]
	v_mfma_f32_16x16x32_bf16 v[18:21], v[154:157], v[178:181], v[18:21]
	v_mfma_f32_16x16x32_bf16 v[6:9], v[146:149], v[186:189], v[6:9]
	v_mfma_f32_16x16x32_bf16 v[2:5], v[154:157], v[186:189], v[2:5]
	v_mfma_f32_16x16x32_bf16 v[54:57], v[150:153], v[166:169], v[54:57]
	v_mfma_f32_16x16x32_bf16 v[50:53], v[158:161], v[166:169], v[50:53]
	v_mfma_f32_16x16x32_bf16 v[38:41], v[150:153], v[174:177], v[38:41]
	v_mfma_f32_16x16x32_bf16 v[34:37], v[158:161], v[174:177], v[34:37]
	v_mfma_f32_16x16x32_bf16 v[22:25], v[150:153], v[182:185], v[22:25]
	v_mfma_f32_16x16x32_bf16 v[18:21], v[158:161], v[182:185], v[18:21]
	v_mfma_f32_16x16x32_bf16 v[6:9], v[150:153], v[190:193], v[6:9]
	v_mfma_f32_16x16x32_bf16 v[2:5], v[158:161], v[190:193], v[2:5]
	s_barrier
	s_add_i32 s48, s48, 2
	s_add_u32 s46, s46, 0x100
	s_addc_u32 s47, s47, 0
	s_add_u32 s18, s18, 0x100
	s_addc_u32 s19, s19, 0
	s_cmp_gt_u32 s48, 29
	.p2align 6
